# final chain with WS2: phase-0 streaming waves use the hand-written double-buffered conversion loop (R0=32768)
# baseline (speedup 1.0000x reference)
; __device__ void p0_xconv(const Args& a) {
;     f16* XH = (f16*)(a.ws + WS_XH); float* SS = (float*)(a.ws + WS_SS);
;     int tid_ = threadIdx.x; asm volatile("" : "+v"(tid_));
;     const int lane = tid_ & 63, wv = tid_ >> 6;
;     const int nwv = (int)gridDim.x * 8;
;     for (int row0 = (int)blockIdx.x * 8 + wv; row0 < MROWS; row0 += 4 * nwv) {
;         f32x4 v[4][4];
; #pragma unroll
;         for (int r = 0; r < 4; ++r) {
;             const int row = row0 + r * nwv;
;             if (row < MROWS) {
;                 const float* src = (row < ROWS_PROMPT) ? a.x_prompt + (size_t)row * DM : a.x_sample + (size_t)(row - ROWS_PROMPT) * DM;
; #pragma unroll
;                 for (int i = 0; i < 4; ++i) v[r][i] = __builtin_nontemporal_load((const f32x4*)(src + i * 256 + lane * 4));
;             }
;         }
; #pragma unroll
;         for (int r = 0; r < 4; ++r) {
;             const int row = row0 + r * nwv;
;             if (row < MROWS) {
;                 float ss = 0.f;
; #pragma unroll
;                 for (int i = 0; i < 4; ++i) {
;                     const f32x4 x = v[r][i];
;                     ss += (x[0] * x[0] + x[1] * x[1]) + (x[2] * x[2] + x[3] * x[3]);
;                     f16x4 h; h[0] = (f16)x[0]; h[1] = (f16)x[1]; h[2] = (f16)x[2]; h[3] = (f16)x[3];
;                     *(f16x4*)(XH + (size_t)row * DM + i * 256 + lane * 4) = h;
.Lws_x:
	v_and_b32_e32 v136, 63, v0
	v_lshrrev_b32_e32 v137, 6, v0
	s_nop 0
	v_readfirstlane_b32 s3, v137
	s_nop 3
	s_lshl_b32 s4, s2, 2
	s_add_i32 s3, s3, s4
	s_add_i32 s3, s3, -4
	s_mov_b64 s[12:13], 1
	v_xor_b32_e32 v130, 1, v136
	v_lshlrev_b32_e32 v130, 2, v130
	v_xor_b32_e32 v131, 2, v136
	v_lshlrev_b32_e32 v131, 2, v131
	v_xor_b32_e32 v132, 4, v136
	v_lshlrev_b32_e32 v132, 2, v132
	v_xor_b32_e32 v133, 8, v136
	v_lshlrev_b32_e32 v133, 2, v133
	v_xor_b32_e32 v134, 16, v136
	v_lshlrev_b32_e32 v134, 2, v134
	v_xor_b32_e32 v135, 32, v136
	v_lshlrev_b32_e32 v135, 2, v135
	v_lshlrev_b32_e32 v140, 4, v136
	v_lshlrev_b32_e32 v144, 3, v136
	v_lshlrev_b32_e32 v186, 2, v136
	v_lshlrev_b32_e32 v141, 4, v136
	v_add_u32_e32 v141, 0x400000, v141
	v_lshlrev_b32_e32 v145, 3, v136
	v_add_u32_e32 v145, 0x200000, v145
	v_lshlrev_b32_e32 v187, 2, v136
	v_add_u32_e32 v187, 0x10000, v187
	v_lshlrev_b32_e32 v142, 4, v136
	v_add_u32_e32 v142, 0x800000, v142
	v_lshlrev_b32_e32 v146, 3, v136
	v_add_u32_e32 v146, 0x400000, v146
	v_lshlrev_b32_e32 v188, 2, v136
	v_add_u32_e32 v188, 0x20000, v188
	v_lshlrev_b32_e32 v143, 4, v136
	v_add_u32_e32 v143, 0xc00000, v143
	v_lshlrev_b32_e32 v147, 3, v136
	v_add_u32_e32 v147, 0x600000, v147
	v_lshlrev_b32_e32 v189, 2, v136
	v_add_u32_e32 v189, 0x30000, v189
	s_add_i32 s6, s3, 0x0
	s_lshl_b32 s6, s6, 12
	s_add_u32 s4, s16, s6
	s_addc_u32 s5, s17, 0
	global_load_dwordx4 v[2:5], v140, s[4:5] nt
	global_load_dwordx4 v[6:9], v140, s[4:5] offset:1024 nt
	global_load_dwordx4 v[10:13], v140, s[4:5] offset:2048 nt
	global_load_dwordx4 v[14:17], v140, s[4:5] offset:3072 nt
	global_load_dwordx4 v[18:21], v141, s[4:5] nt
	global_load_dwordx4 v[22:25], v141, s[4:5] offset:1024 nt
	global_load_dwordx4 v[26:29], v141, s[4:5] offset:2048 nt
	global_load_dwordx4 v[30:33], v141, s[4:5] offset:3072 nt
	global_load_dwordx4 v[34:37], v142, s[4:5] nt
	global_load_dwordx4 v[38:41], v142, s[4:5] offset:1024 nt
	global_load_dwordx4 v[42:45], v142, s[4:5] offset:2048 nt
	global_load_dwordx4 v[46:49], v142, s[4:5] offset:3072 nt
	global_load_dwordx4 v[50:53], v143, s[4:5] nt
	global_load_dwordx4 v[54:57], v143, s[4:5] offset:1024 nt
	global_load_dwordx4 v[58:61], v143, s[4:5] offset:2048 nt
	global_load_dwordx4 v[62:65], v143, s[4:5] offset:3072 nt
	s_add_i32 s6, s3, 0x1000
	s_lshl_b32 s6, s6, 12
	s_add_u32 s4, s16, s6
	s_addc_u32 s5, s17, 0
	global_load_dwordx4 v[66:69], v140, s[4:5] nt
	global_load_dwordx4 v[70:73], v140, s[4:5] offset:1024 nt
	global_load_dwordx4 v[74:77], v140, s[4:5] offset:2048 nt
	global_load_dwordx4 v[78:81], v140, s[4:5] offset:3072 nt
	global_load_dwordx4 v[82:85], v141, s[4:5] nt
	global_load_dwordx4 v[86:89], v141, s[4:5] offset:1024 nt
	global_load_dwordx4 v[90:93], v141, s[4:5] offset:2048 nt
	global_load_dwordx4 v[94:97], v141, s[4:5] offset:3072 nt
	global_load_dwordx4 v[98:101], v142, s[4:5] nt
	global_load_dwordx4 v[102:105], v142, s[4:5] offset:1024 nt
	global_load_dwordx4 v[106:109], v142, s[4:5] offset:2048 nt
	global_load_dwordx4 v[110:113], v142, s[4:5] offset:3072 nt
	global_load_dwordx4 v[114:117], v143, s[4:5] nt
	global_load_dwordx4 v[118:121], v143, s[4:5] offset:1024 nt
	global_load_dwordx4 v[122:125], v143, s[4:5] offset:2048 nt
	global_load_dwordx4 v[126:129], v143, s[4:5] offset:3072 nt
	s_waitcnt vmcnt(16)
	s_add_i32 s6, s3, 0x0
	s_lshl_b32 s7, s6, 11
	s_add_u32 s10, s40, s7
	s_addc_u32 s11, s41, 0
	s_lshl_b32 s7, s6, 6
	s_add_u32 s6, s40, s7
	s_addc_u32 s7, s41, 0
	s_add_u32 s6, s6, 0x1f800000
	s_addc_u32 s7, s7, 0
	v_mul_f32_e32 v150, v3, v3
	v_mul_f32_e32 v151, v5, v5
	v_fmac_f32_e32 v150, v2, v2
	v_fmac_f32_e32 v151, v4, v4
	v_add_f32_e32 v160, v150, v151
	v_cvt_pk_f16_f32 v170, v2, v3
	v_cvt_pk_f16_f32 v171, v4, v5
	v_mul_f32_e32 v150, v7, v7
	v_mul_f32_e32 v151, v9, v9
	v_fmac_f32_e32 v150, v6, v6
	v_fmac_f32_e32 v151, v8, v8
	v_add_f32_e32 v152, v150, v151
	v_add_f32_e32 v160, v160, v152
	v_cvt_pk_f16_f32 v172, v6, v7
	v_cvt_pk_f16_f32 v173, v8, v9
	v_mul_f32_e32 v150, v11, v11
	v_mul_f32_e32 v151, v13, v13
	v_fmac_f32_e32 v150, v10, v10
	v_fmac_f32_e32 v151, v12, v12
	v_add_f32_e32 v152, v150, v151
	v_add_f32_e32 v160, v160, v152
	v_cvt_pk_f16_f32 v174, v10, v11
	v_cvt_pk_f16_f32 v175, v12, v13
	v_mul_f32_e32 v150, v15, v15
	v_mul_f32_e32 v151, v17, v17
	v_fmac_f32_e32 v150, v14, v14
	v_fmac_f32_e32 v151, v16, v16
	v_add_f32_e32 v152, v150, v151
	v_add_f32_e32 v160, v160, v152
	v_cvt_pk_f16_f32 v176, v14, v15
	v_cvt_pk_f16_f32 v177, v16, v17
	global_store_dwordx2 v144, v[170:171], s[10:11]
	global_store_dwordx2 v144, v[172:173], s[10:11] offset:512
	global_store_dwordx2 v144, v[174:175], s[10:11] offset:1024
	global_store_dwordx2 v144, v[176:177], s[10:11] offset:1536
	v_mul_f32_e32 v150, v19, v19
	v_mul_f32_e32 v151, v21, v21
	v_fmac_f32_e32 v150, v18, v18
	v_fmac_f32_e32 v151, v20, v20
	v_add_f32_e32 v161, v150, v151
	v_cvt_pk_f16_f32 v178, v18, v19
	v_cvt_pk_f16_f32 v179, v20, v21
	v_mul_f32_e32 v150, v23, v23
	v_mul_f32_e32 v151, v25, v25
	v_fmac_f32_e32 v150, v22, v22
	v_fmac_f32_e32 v151, v24, v24
	v_add_f32_e32 v152, v150, v151
	v_add_f32_e32 v161, v161, v152
	v_cvt_pk_f16_f32 v180, v22, v23
	v_cvt_pk_f16_f32 v181, v24, v25
	v_mul_f32_e32 v150, v27, v27
	v_mul_f32_e32 v151, v29, v29
	v_fmac_f32_e32 v150, v26, v26
	v_fmac_f32_e32 v151, v28, v28
	v_add_f32_e32 v152, v150, v151
	v_add_f32_e32 v161, v161, v152
	v_cvt_pk_f16_f32 v182, v26, v27
	v_cvt_pk_f16_f32 v183, v28, v29
	v_mul_f32_e32 v150, v31, v31
	v_mul_f32_e32 v151, v33, v33
	v_fmac_f32_e32 v150, v30, v30
	v_fmac_f32_e32 v151, v32, v32
	v_add_f32_e32 v152, v150, v151
	v_add_f32_e32 v161, v161, v152
	v_cvt_pk_f16_f32 v184, v30, v31
; __device__ void p0_xconv(const Args& a) {
;     ...
; #pragma unroll
;         for (int r = 0; r < 4; ++r) {
;             const int row = row0 + r * nwv;
;             if (row < MROWS) {
;                 float ss = 0.f;
; #pragma unroll
;                 for (int i = 0; i < 4; ++i) {
;                     const f32x4 x = v[r][i];
;                     ss += (x[0] * x[0] + x[1] * x[1]) + (x[2] * x[2] + x[3] * x[3]);
;                     f16x4 h; h[0] = (f16)x[0]; h[1] = (f16)x[1]; h[2] = (f16)x[2]; h[3] = (f16)x[3];
;                     *(f16x4*)(XH + (size_t)row * DM + i * 256 + lane * 4) = h;
;                 }
; #pragma unroll
;                 for (int o = 1; o < 64; o <<= 1) ss += __shfl_xor(ss, o);
;                 if (lane < 16) SS[(size_t)row * 16 + lane] = (lane == 0) ? ss : 0.f;
;             }
	v_cvt_pk_f16_f32 v185, v32, v33
	global_store_dwordx2 v145, v[178:179], s[10:11]
	global_store_dwordx2 v145, v[180:181], s[10:11] offset:512
	global_store_dwordx2 v145, v[182:183], s[10:11] offset:1024
	global_store_dwordx2 v145, v[184:185], s[10:11] offset:1536
	v_mul_f32_e32 v150, v35, v35
	v_mul_f32_e32 v151, v37, v37
	v_fmac_f32_e32 v150, v34, v34
	v_fmac_f32_e32 v151, v36, v36
	v_add_f32_e32 v162, v150, v151
	v_cvt_pk_f16_f32 v170, v34, v35
	v_cvt_pk_f16_f32 v171, v36, v37
	v_mul_f32_e32 v150, v39, v39
	v_mul_f32_e32 v151, v41, v41
	v_fmac_f32_e32 v150, v38, v38
	v_fmac_f32_e32 v151, v40, v40
	v_add_f32_e32 v152, v150, v151
	v_add_f32_e32 v162, v162, v152
	v_cvt_pk_f16_f32 v172, v38, v39
	v_cvt_pk_f16_f32 v173, v40, v41
	v_mul_f32_e32 v150, v43, v43
	v_mul_f32_e32 v151, v45, v45
	v_fmac_f32_e32 v150, v42, v42
	v_fmac_f32_e32 v151, v44, v44
	v_add_f32_e32 v152, v150, v151
	v_add_f32_e32 v162, v162, v152
	v_cvt_pk_f16_f32 v174, v42, v43
	v_cvt_pk_f16_f32 v175, v44, v45
	v_mul_f32_e32 v150, v47, v47
	v_mul_f32_e32 v151, v49, v49
	v_fmac_f32_e32 v150, v46, v46
	v_fmac_f32_e32 v151, v48, v48
	v_add_f32_e32 v152, v150, v151
	v_add_f32_e32 v162, v162, v152
	v_cvt_pk_f16_f32 v176, v46, v47
	v_cvt_pk_f16_f32 v177, v48, v49
	global_store_dwordx2 v146, v[170:171], s[10:11]
	global_store_dwordx2 v146, v[172:173], s[10:11] offset:512
	global_store_dwordx2 v146, v[174:175], s[10:11] offset:1024
	global_store_dwordx2 v146, v[176:177], s[10:11] offset:1536
	v_mul_f32_e32 v150, v51, v51
	v_mul_f32_e32 v151, v53, v53
	v_fmac_f32_e32 v150, v50, v50
	v_fmac_f32_e32 v151, v52, v52
	v_add_f32_e32 v163, v150, v151
	v_cvt_pk_f16_f32 v178, v50, v51
	v_cvt_pk_f16_f32 v179, v52, v53
	v_mul_f32_e32 v150, v55, v55
	v_mul_f32_e32 v151, v57, v57
	v_fmac_f32_e32 v150, v54, v54
	v_fmac_f32_e32 v151, v56, v56
	v_add_f32_e32 v152, v150, v151
	v_add_f32_e32 v163, v163, v152
	v_cvt_pk_f16_f32 v180, v54, v55
	v_cvt_pk_f16_f32 v181, v56, v57
	v_mul_f32_e32 v150, v59, v59
	v_mul_f32_e32 v151, v61, v61
	v_fmac_f32_e32 v150, v58, v58
	v_fmac_f32_e32 v151, v60, v60
	v_add_f32_e32 v152, v150, v151
	v_add_f32_e32 v163, v163, v152
	v_cvt_pk_f16_f32 v182, v58, v59
	v_cvt_pk_f16_f32 v183, v60, v61
	v_mul_f32_e32 v150, v63, v63
	v_mul_f32_e32 v151, v65, v65
	v_fmac_f32_e32 v150, v62, v62
	v_fmac_f32_e32 v151, v64, v64
	v_add_f32_e32 v152, v150, v151
	v_add_f32_e32 v163, v163, v152
	v_cvt_pk_f16_f32 v184, v62, v63
	v_cvt_pk_f16_f32 v185, v64, v65
	global_store_dwordx2 v147, v[178:179], s[10:11]
	global_store_dwordx2 v147, v[180:181], s[10:11] offset:512
	global_store_dwordx2 v147, v[182:183], s[10:11] offset:1024
	global_store_dwordx2 v147, v[184:185], s[10:11] offset:1536
	ds_bpermute_b32 v164, v130, v160
	ds_bpermute_b32 v165, v130, v161
	ds_bpermute_b32 v166, v130, v162
	ds_bpermute_b32 v167, v130, v163
	s_waitcnt lgkmcnt(0)
	v_add_f32_e32 v160, v160, v164
	v_add_f32_e32 v161, v161, v165
	v_add_f32_e32 v162, v162, v166
	v_add_f32_e32 v163, v163, v167
	ds_bpermute_b32 v164, v131, v160
	ds_bpermute_b32 v165, v131, v161
	ds_bpermute_b32 v166, v131, v162
	ds_bpermute_b32 v167, v131, v163
	s_waitcnt lgkmcnt(0)
	v_add_f32_e32 v160, v160, v164
	v_add_f32_e32 v161, v161, v165
	v_add_f32_e32 v162, v162, v166
	v_add_f32_e32 v163, v163, v167
	ds_bpermute_b32 v164, v132, v160
	ds_bpermute_b32 v165, v132, v161
	ds_bpermute_b32 v166, v132, v162
	ds_bpermute_b32 v167, v132, v163
	s_waitcnt lgkmcnt(0)
	v_add_f32_e32 v160, v160, v164
	v_add_f32_e32 v161, v161, v165
	v_add_f32_e32 v162, v162, v166
	v_add_f32_e32 v163, v163, v167
	ds_bpermute_b32 v164, v133, v160
	ds_bpermute_b32 v165, v133, v161
	ds_bpermute_b32 v166, v133, v162
	ds_bpermute_b32 v167, v133, v163
	s_waitcnt lgkmcnt(0)
	v_add_f32_e32 v160, v160, v164
	v_add_f32_e32 v161, v161, v165
	v_add_f32_e32 v162, v162, v166
	v_add_f32_e32 v163, v163, v167
	ds_bpermute_b32 v164, v134, v160
	ds_bpermute_b32 v165, v134, v161
	ds_bpermute_b32 v166, v134, v162
	ds_bpermute_b32 v167, v134, v163
	s_waitcnt lgkmcnt(0)
	v_add_f32_e32 v160, v160, v164
	v_add_f32_e32 v161, v161, v165
	v_add_f32_e32 v162, v162, v166
	v_add_f32_e32 v163, v163, v167
	ds_bpermute_b32 v164, v135, v160
	ds_bpermute_b32 v165, v135, v161
	ds_bpermute_b32 v166, v135, v162
	ds_bpermute_b32 v167, v135, v163
	s_waitcnt lgkmcnt(0)
	v_add_f32_e32 v160, v160, v164
	v_add_f32_e32 v161, v161, v165
	v_add_f32_e32 v162, v162, v166
	v_add_f32_e32 v163, v163, v167
	v_cndmask_b32_e64 v164, 0, v160, s[12:13]
	v_cndmask_b32_e64 v165, 0, v161, s[12:13]
	v_cndmask_b32_e64 v166, 0, v162, s[12:13]
	v_cndmask_b32_e64 v167, 0, v163, s[12:13]
	s_mov_b64 exec, 0xffff
	global_store_dword v186, v164, s[6:7]
	global_store_dword v187, v165, s[6:7]
	global_store_dword v188, v166, s[6:7]
	global_store_dword v189, v167, s[6:7]
	s_mov_b64 exec, -1
	s_add_i32 s6, s3, 0x2000
	s_lshl_b32 s6, s6, 12
	s_add_u32 s4, s16, s6
	s_addc_u32 s5, s17, 0
	global_load_dwordx4 v[2:5], v140, s[4:5] nt
	global_load_dwordx4 v[6:9], v140, s[4:5] offset:1024 nt
	global_load_dwordx4 v[10:13], v140, s[4:5] offset:2048 nt
	global_load_dwordx4 v[14:17], v140, s[4:5] offset:3072 nt
	global_load_dwordx4 v[18:21], v141, s[4:5] nt
	global_load_dwordx4 v[22:25], v141, s[4:5] offset:1024 nt
	global_load_dwordx4 v[26:29], v141, s[4:5] offset:2048 nt
	global_load_dwordx4 v[30:33], v141, s[4:5] offset:3072 nt
	global_load_dwordx4 v[34:37], v142, s[4:5] nt
	global_load_dwordx4 v[38:41], v142, s[4:5] offset:1024 nt
	global_load_dwordx4 v[42:45], v142, s[4:5] offset:2048 nt
	global_load_dwordx4 v[46:49], v142, s[4:5] offset:3072 nt
	global_load_dwordx4 v[50:53], v143, s[4:5] nt
	global_load_dwordx4 v[54:57], v143, s[4:5] offset:1024 nt
	global_load_dwordx4 v[58:61], v143, s[4:5] offset:2048 nt
	global_load_dwordx4 v[62:65], v143, s[4:5] offset:3072 nt
	s_waitcnt vmcnt(36)
; __device__ void p0_xconv(const Args& a) {
;     ...
; #pragma unroll
;         for (int r = 0; r < 4; ++r) {
;             const int row = row0 + r * nwv;
;             if (row < MROWS) {
;                 float ss = 0.f;
; #pragma unroll
;                 for (int i = 0; i < 4; ++i) {
;                     const f32x4 x = v[r][i];
;                     ss += (x[0] * x[0] + x[1] * x[1]) + (x[2] * x[2] + x[3] * x[3]);
;                     f16x4 h; h[0] = (f16)x[0]; h[1] = (f16)x[1]; h[2] = (f16)x[2]; h[3] = (f16)x[3];
;                     *(f16x4*)(XH + (size_t)row * DM + i * 256 + lane * 4) = h;
;                 }
; #pragma unroll
;                 for (int o = 1; o < 64; o <<= 1) ss += __shfl_xor(ss, o);
	s_add_i32 s6, s3, 0x1000
	s_lshl_b32 s7, s6, 11
	s_add_u32 s10, s40, s7
	s_addc_u32 s11, s41, 0
	s_lshl_b32 s7, s6, 6
	s_add_u32 s6, s40, s7
	s_addc_u32 s7, s41, 0
	s_add_u32 s6, s6, 0x1f800000
	s_addc_u32 s7, s7, 0
	v_mul_f32_e32 v150, v67, v67
	v_mul_f32_e32 v151, v69, v69
	v_fmac_f32_e32 v150, v66, v66
	v_fmac_f32_e32 v151, v68, v68
	v_add_f32_e32 v160, v150, v151
	v_cvt_pk_f16_f32 v170, v66, v67
	v_cvt_pk_f16_f32 v171, v68, v69
	v_mul_f32_e32 v150, v71, v71
	v_mul_f32_e32 v151, v73, v73
	v_fmac_f32_e32 v150, v70, v70
	v_fmac_f32_e32 v151, v72, v72
	v_add_f32_e32 v152, v150, v151
	v_add_f32_e32 v160, v160, v152
	v_cvt_pk_f16_f32 v172, v70, v71
	v_cvt_pk_f16_f32 v173, v72, v73
	v_mul_f32_e32 v150, v75, v75
	v_mul_f32_e32 v151, v77, v77
	v_fmac_f32_e32 v150, v74, v74
	v_fmac_f32_e32 v151, v76, v76
	v_add_f32_e32 v152, v150, v151
	v_add_f32_e32 v160, v160, v152
	v_cvt_pk_f16_f32 v174, v74, v75
	v_cvt_pk_f16_f32 v175, v76, v77
	v_mul_f32_e32 v150, v79, v79
	v_mul_f32_e32 v151, v81, v81
	v_fmac_f32_e32 v150, v78, v78
	v_fmac_f32_e32 v151, v80, v80
	v_add_f32_e32 v152, v150, v151
	v_add_f32_e32 v160, v160, v152
	v_cvt_pk_f16_f32 v176, v78, v79
	v_cvt_pk_f16_f32 v177, v80, v81
	global_store_dwordx2 v144, v[170:171], s[10:11]
	global_store_dwordx2 v144, v[172:173], s[10:11] offset:512
	global_store_dwordx2 v144, v[174:175], s[10:11] offset:1024
	global_store_dwordx2 v144, v[176:177], s[10:11] offset:1536
	v_mul_f32_e32 v150, v83, v83
	v_mul_f32_e32 v151, v85, v85
	v_fmac_f32_e32 v150, v82, v82
	v_fmac_f32_e32 v151, v84, v84
	v_add_f32_e32 v161, v150, v151
	v_cvt_pk_f16_f32 v178, v82, v83
	v_cvt_pk_f16_f32 v179, v84, v85
	v_mul_f32_e32 v150, v87, v87
	v_mul_f32_e32 v151, v89, v89
	v_fmac_f32_e32 v150, v86, v86
	v_fmac_f32_e32 v151, v88, v88
	v_add_f32_e32 v152, v150, v151
	v_add_f32_e32 v161, v161, v152
	v_cvt_pk_f16_f32 v180, v86, v87
	v_cvt_pk_f16_f32 v181, v88, v89
	v_mul_f32_e32 v150, v91, v91
	v_mul_f32_e32 v151, v93, v93
	v_fmac_f32_e32 v150, v90, v90
	v_fmac_f32_e32 v151, v92, v92
	v_add_f32_e32 v152, v150, v151
	v_add_f32_e32 v161, v161, v152
	v_cvt_pk_f16_f32 v182, v90, v91
	v_cvt_pk_f16_f32 v183, v92, v93
	v_mul_f32_e32 v150, v95, v95
	v_mul_f32_e32 v151, v97, v97
	v_fmac_f32_e32 v150, v94, v94
	v_fmac_f32_e32 v151, v96, v96
	v_add_f32_e32 v152, v150, v151
	v_add_f32_e32 v161, v161, v152
	v_cvt_pk_f16_f32 v184, v94, v95
	v_cvt_pk_f16_f32 v185, v96, v97
	global_store_dwordx2 v145, v[178:179], s[10:11]
	global_store_dwordx2 v145, v[180:181], s[10:11] offset:512
	global_store_dwordx2 v145, v[182:183], s[10:11] offset:1024
	global_store_dwordx2 v145, v[184:185], s[10:11] offset:1536
	v_mul_f32_e32 v150, v99, v99
	v_mul_f32_e32 v151, v101, v101
	v_fmac_f32_e32 v150, v98, v98
	v_fmac_f32_e32 v151, v100, v100
	v_add_f32_e32 v162, v150, v151
	v_cvt_pk_f16_f32 v170, v98, v99
	v_cvt_pk_f16_f32 v171, v100, v101
	v_mul_f32_e32 v150, v103, v103
	v_mul_f32_e32 v151, v105, v105
	v_fmac_f32_e32 v150, v102, v102
	v_fmac_f32_e32 v151, v104, v104
	v_add_f32_e32 v152, v150, v151
	v_add_f32_e32 v162, v162, v152
	v_cvt_pk_f16_f32 v172, v102, v103
	v_cvt_pk_f16_f32 v173, v104, v105
	v_mul_f32_e32 v150, v107, v107
	v_mul_f32_e32 v151, v109, v109
	v_fmac_f32_e32 v150, v106, v106
	v_fmac_f32_e32 v151, v108, v108
	v_add_f32_e32 v152, v150, v151
	v_add_f32_e32 v162, v162, v152
	v_cvt_pk_f16_f32 v174, v106, v107
	v_cvt_pk_f16_f32 v175, v108, v109
	v_mul_f32_e32 v150, v111, v111
	v_mul_f32_e32 v151, v113, v113
	v_fmac_f32_e32 v150, v110, v110
	v_fmac_f32_e32 v151, v112, v112
	v_add_f32_e32 v152, v150, v151
	v_add_f32_e32 v162, v162, v152
	v_cvt_pk_f16_f32 v176, v110, v111
	v_cvt_pk_f16_f32 v177, v112, v113
	global_store_dwordx2 v146, v[170:171], s[10:11]
	global_store_dwordx2 v146, v[172:173], s[10:11] offset:512
	global_store_dwordx2 v146, v[174:175], s[10:11] offset:1024
	global_store_dwordx2 v146, v[176:177], s[10:11] offset:1536
	v_mul_f32_e32 v150, v115, v115
	v_mul_f32_e32 v151, v117, v117
	v_fmac_f32_e32 v150, v114, v114
	v_fmac_f32_e32 v151, v116, v116
	v_add_f32_e32 v163, v150, v151
	v_cvt_pk_f16_f32 v178, v114, v115
	v_cvt_pk_f16_f32 v179, v116, v117
	v_mul_f32_e32 v150, v119, v119
	v_mul_f32_e32 v151, v121, v121
	v_fmac_f32_e32 v150, v118, v118
	v_fmac_f32_e32 v151, v120, v120
	v_add_f32_e32 v152, v150, v151
	v_add_f32_e32 v163, v163, v152
	v_cvt_pk_f16_f32 v180, v118, v119
	v_cvt_pk_f16_f32 v181, v120, v121
	v_mul_f32_e32 v150, v123, v123
	v_mul_f32_e32 v151, v125, v125
	v_fmac_f32_e32 v150, v122, v122
	v_fmac_f32_e32 v151, v124, v124
	v_add_f32_e32 v152, v150, v151
	v_add_f32_e32 v163, v163, v152
	v_cvt_pk_f16_f32 v182, v122, v123
	v_cvt_pk_f16_f32 v183, v124, v125
	v_mul_f32_e32 v150, v127, v127
	v_mul_f32_e32 v151, v129, v129
	v_fmac_f32_e32 v150, v126, v126
	v_fmac_f32_e32 v151, v128, v128
	v_add_f32_e32 v152, v150, v151
	v_add_f32_e32 v163, v163, v152
	v_cvt_pk_f16_f32 v184, v126, v127
	v_cvt_pk_f16_f32 v185, v128, v129
	global_store_dwordx2 v147, v[178:179], s[10:11]
	global_store_dwordx2 v147, v[180:181], s[10:11] offset:512
	global_store_dwordx2 v147, v[182:183], s[10:11] offset:1024
	global_store_dwordx2 v147, v[184:185], s[10:11] offset:1536
	ds_bpermute_b32 v164, v130, v160
	ds_bpermute_b32 v165, v130, v161
	ds_bpermute_b32 v166, v130, v162
	ds_bpermute_b32 v167, v130, v163
	s_waitcnt lgkmcnt(0)
	v_add_f32_e32 v160, v160, v164
	v_add_f32_e32 v161, v161, v165
	v_add_f32_e32 v162, v162, v166
	v_add_f32_e32 v163, v163, v167
	ds_bpermute_b32 v164, v131, v160
	ds_bpermute_b32 v165, v131, v161
	ds_bpermute_b32 v166, v131, v162
	ds_bpermute_b32 v167, v131, v163
	s_waitcnt lgkmcnt(0)
; __device__ void p0_xconv(const Args& a) {
;     f16* XH = (f16*)(a.ws + WS_XH); float* SS = (float*)(a.ws + WS_SS);
;     int tid_ = threadIdx.x; asm volatile("" : "+v"(tid_));
;     const int lane = tid_ & 63, wv = tid_ >> 6;
;     const int nwv = (int)gridDim.x * 8;
;     for (int row0 = (int)blockIdx.x * 8 + wv; row0 < MROWS; row0 += 4 * nwv) {
;         f32x4 v[4][4];
; #pragma unroll
;         for (int r = 0; r < 4; ++r) {
;             const int row = row0 + r * nwv;
;             if (row < MROWS) {
;                 const float* src = (row < ROWS_PROMPT) ? a.x_prompt + (size_t)row * DM : a.x_sample + (size_t)(row - ROWS_PROMPT) * DM;
; #pragma unroll
;                 for (int i = 0; i < 4; ++i) v[r][i] = __builtin_nontemporal_load((const f32x4*)(src + i * 256 + lane * 4));
;             }
;         }
; #pragma unroll
;         for (int r = 0; r < 4; ++r) {
;             const int row = row0 + r * nwv;
;             if (row < MROWS) {
;                 float ss = 0.f;
; #pragma unroll
;                 for (int i = 0; i < 4; ++i) {
;                     const f32x4 x = v[r][i];
;                     ss += (x[0] * x[0] + x[1] * x[1]) + (x[2] * x[2] + x[3] * x[3]);
;                     f16x4 h; h[0] = (f16)x[0]; h[1] = (f16)x[1]; h[2] = (f16)x[2]; h[3] = (f16)x[3];
;                     *(f16x4*)(XH + (size_t)row * DM + i * 256 + lane * 4) = h;
;                 }
; #pragma unroll
;                 for (int o = 1; o < 64; o <<= 1) ss += __shfl_xor(ss, o);
;                 if (lane < 16) SS[(size_t)row * 16 + lane] = (lane == 0) ? ss : 0.f;
;             }
	v_add_f32_e32 v160, v160, v164
	v_add_f32_e32 v161, v161, v165
	v_add_f32_e32 v162, v162, v166
	v_add_f32_e32 v163, v163, v167
	ds_bpermute_b32 v164, v132, v160
	ds_bpermute_b32 v165, v132, v161
	ds_bpermute_b32 v166, v132, v162
	ds_bpermute_b32 v167, v132, v163
	s_waitcnt lgkmcnt(0)
	v_add_f32_e32 v160, v160, v164
	v_add_f32_e32 v161, v161, v165
	v_add_f32_e32 v162, v162, v166
	v_add_f32_e32 v163, v163, v167
	ds_bpermute_b32 v164, v133, v160
	ds_bpermute_b32 v165, v133, v161
	ds_bpermute_b32 v166, v133, v162
	ds_bpermute_b32 v167, v133, v163
	s_waitcnt lgkmcnt(0)
	v_add_f32_e32 v160, v160, v164
	v_add_f32_e32 v161, v161, v165
	v_add_f32_e32 v162, v162, v166
	v_add_f32_e32 v163, v163, v167
	ds_bpermute_b32 v164, v134, v160
	ds_bpermute_b32 v165, v134, v161
	ds_bpermute_b32 v166, v134, v162
	ds_bpermute_b32 v167, v134, v163
	s_waitcnt lgkmcnt(0)
	v_add_f32_e32 v160, v160, v164
	v_add_f32_e32 v161, v161, v165
	v_add_f32_e32 v162, v162, v166
	v_add_f32_e32 v163, v163, v167
	ds_bpermute_b32 v164, v135, v160
	ds_bpermute_b32 v165, v135, v161
	ds_bpermute_b32 v166, v135, v162
	ds_bpermute_b32 v167, v135, v163
	s_waitcnt lgkmcnt(0)
	v_add_f32_e32 v160, v160, v164
	v_add_f32_e32 v161, v161, v165
	v_add_f32_e32 v162, v162, v166
	v_add_f32_e32 v163, v163, v167
	v_cndmask_b32_e64 v164, 0, v160, s[12:13]
	v_cndmask_b32_e64 v165, 0, v161, s[12:13]
	v_cndmask_b32_e64 v166, 0, v162, s[12:13]
	v_cndmask_b32_e64 v167, 0, v163, s[12:13]
	s_mov_b64 exec, 0xffff
	global_store_dword v186, v164, s[6:7]
	global_store_dword v187, v165, s[6:7]
	global_store_dword v188, v166, s[6:7]
	global_store_dword v189, v167, s[6:7]
	s_mov_b64 exec, -1
	s_add_i32 s6, s3, 0x3000
	s_lshl_b32 s6, s6, 12
	s_add_u32 s4, s16, s6
	s_addc_u32 s5, s17, 0
	global_load_dwordx4 v[66:69], v140, s[4:5] nt
	global_load_dwordx4 v[70:73], v140, s[4:5] offset:1024 nt
	global_load_dwordx4 v[74:77], v140, s[4:5] offset:2048 nt
	global_load_dwordx4 v[78:81], v140, s[4:5] offset:3072 nt
	global_load_dwordx4 v[82:85], v141, s[4:5] nt
	global_load_dwordx4 v[86:89], v141, s[4:5] offset:1024 nt
	global_load_dwordx4 v[90:93], v141, s[4:5] offset:2048 nt
	global_load_dwordx4 v[94:97], v141, s[4:5] offset:3072 nt
	global_load_dwordx4 v[98:101], v142, s[4:5] nt
	global_load_dwordx4 v[102:105], v142, s[4:5] offset:1024 nt
	global_load_dwordx4 v[106:109], v142, s[4:5] offset:2048 nt
	global_load_dwordx4 v[110:113], v142, s[4:5] offset:3072 nt
	global_load_dwordx4 v[114:117], v143, s[4:5] nt
	global_load_dwordx4 v[118:121], v143, s[4:5] offset:1024 nt
	global_load_dwordx4 v[122:125], v143, s[4:5] offset:2048 nt
	global_load_dwordx4 v[126:129], v143, s[4:5] offset:3072 nt
	s_waitcnt vmcnt(36)
	s_add_i32 s6, s3, 0x2000
	s_lshl_b32 s7, s6, 11
	s_add_u32 s10, s40, s7
	s_addc_u32 s11, s41, 0
	s_lshl_b32 s7, s6, 6
	s_add_u32 s6, s40, s7
	s_addc_u32 s7, s41, 0
	s_add_u32 s6, s6, 0x1f800000
	s_addc_u32 s7, s7, 0
	v_mul_f32_e32 v150, v3, v3
	v_mul_f32_e32 v151, v5, v5
	v_fmac_f32_e32 v150, v2, v2
	v_fmac_f32_e32 v151, v4, v4
	v_add_f32_e32 v160, v150, v151
	v_cvt_pk_f16_f32 v170, v2, v3
	v_cvt_pk_f16_f32 v171, v4, v5
	v_mul_f32_e32 v150, v7, v7
	v_mul_f32_e32 v151, v9, v9
	v_fmac_f32_e32 v150, v6, v6
	v_fmac_f32_e32 v151, v8, v8
	v_add_f32_e32 v152, v150, v151
	v_add_f32_e32 v160, v160, v152
	v_cvt_pk_f16_f32 v172, v6, v7
	v_cvt_pk_f16_f32 v173, v8, v9
	v_mul_f32_e32 v150, v11, v11
	v_mul_f32_e32 v151, v13, v13
	v_fmac_f32_e32 v150, v10, v10
	v_fmac_f32_e32 v151, v12, v12
	v_add_f32_e32 v152, v150, v151
	v_add_f32_e32 v160, v160, v152
	v_cvt_pk_f16_f32 v174, v10, v11
	v_cvt_pk_f16_f32 v175, v12, v13
	v_mul_f32_e32 v150, v15, v15
	v_mul_f32_e32 v151, v17, v17
	v_fmac_f32_e32 v150, v14, v14
	v_fmac_f32_e32 v151, v16, v16
	v_add_f32_e32 v152, v150, v151
	v_add_f32_e32 v160, v160, v152
	v_cvt_pk_f16_f32 v176, v14, v15
	v_cvt_pk_f16_f32 v177, v16, v17
	global_store_dwordx2 v144, v[170:171], s[10:11]
	global_store_dwordx2 v144, v[172:173], s[10:11] offset:512
	global_store_dwordx2 v144, v[174:175], s[10:11] offset:1024
	global_store_dwordx2 v144, v[176:177], s[10:11] offset:1536
	v_mul_f32_e32 v150, v19, v19
	v_mul_f32_e32 v151, v21, v21
	v_fmac_f32_e32 v150, v18, v18
	v_fmac_f32_e32 v151, v20, v20
	v_add_f32_e32 v161, v150, v151
	v_cvt_pk_f16_f32 v178, v18, v19
	v_cvt_pk_f16_f32 v179, v20, v21
	v_mul_f32_e32 v150, v23, v23
	v_mul_f32_e32 v151, v25, v25
	v_fmac_f32_e32 v150, v22, v22
	v_fmac_f32_e32 v151, v24, v24
	v_add_f32_e32 v152, v150, v151
	v_add_f32_e32 v161, v161, v152
	v_cvt_pk_f16_f32 v180, v22, v23
	v_cvt_pk_f16_f32 v181, v24, v25
	v_mul_f32_e32 v150, v27, v27
	v_mul_f32_e32 v151, v29, v29
	v_fmac_f32_e32 v150, v26, v26
	v_fmac_f32_e32 v151, v28, v28
	v_add_f32_e32 v152, v150, v151
	v_add_f32_e32 v161, v161, v152
	v_cvt_pk_f16_f32 v182, v26, v27
	v_cvt_pk_f16_f32 v183, v28, v29
	v_mul_f32_e32 v150, v31, v31
	v_mul_f32_e32 v151, v33, v33
	v_fmac_f32_e32 v150, v30, v30
	v_fmac_f32_e32 v151, v32, v32
	v_add_f32_e32 v152, v150, v151
	v_add_f32_e32 v161, v161, v152
	v_cvt_pk_f16_f32 v184, v30, v31
	v_cvt_pk_f16_f32 v185, v32, v33
	global_store_dwordx2 v145, v[178:179], s[10:11]
	global_store_dwordx2 v145, v[180:181], s[10:11] offset:512
	global_store_dwordx2 v145, v[182:183], s[10:11] offset:1024
	global_store_dwordx2 v145, v[184:185], s[10:11] offset:1536
	v_mul_f32_e32 v150, v35, v35
	v_mul_f32_e32 v151, v37, v37
	v_fmac_f32_e32 v150, v34, v34
	v_fmac_f32_e32 v151, v36, v36
	v_add_f32_e32 v162, v150, v151
	v_cvt_pk_f16_f32 v170, v34, v35
	v_cvt_pk_f16_f32 v171, v36, v37
	v_mul_f32_e32 v150, v39, v39
	v_mul_f32_e32 v151, v41, v41
	v_fmac_f32_e32 v150, v38, v38
	v_fmac_f32_e32 v151, v40, v40
	v_add_f32_e32 v152, v150, v151
; __device__ void p0_xconv(const Args& a) {
;     ...
;                 const float* src = (row < ROWS_PROMPT) ? a.x_prompt + (size_t)row * DM : a.x_sample + (size_t)(row - ROWS_PROMPT) * DM;
; #pragma unroll
;                 for (int i = 0; i < 4; ++i) v[r][i] = __builtin_nontemporal_load((const f32x4*)(src + i * 256 + lane * 4));
;     ...
;         for (int r = 0; r < 4; ++r) {
;             const int row = row0 + r * nwv;
;             if (row < MROWS) {
;                 float ss = 0.f;
; #pragma unroll
;                 for (int i = 0; i < 4; ++i) {
;                     const f32x4 x = v[r][i];
;                     ss += (x[0] * x[0] + x[1] * x[1]) + (x[2] * x[2] + x[3] * x[3]);
;                     f16x4 h; h[0] = (f16)x[0]; h[1] = (f16)x[1]; h[2] = (f16)x[2]; h[3] = (f16)x[3];
;                     *(f16x4*)(XH + (size_t)row * DM + i * 256 + lane * 4) = h;
;                 }
; #pragma unroll
;                 for (int o = 1; o < 64; o <<= 1) ss += __shfl_xor(ss, o);
;                 if (lane < 16) SS[(size_t)row * 16 + lane] = (lane == 0) ? ss : 0.f;
	v_add_f32_e32 v162, v162, v152
	v_cvt_pk_f16_f32 v172, v38, v39
	v_cvt_pk_f16_f32 v173, v40, v41
	v_mul_f32_e32 v150, v43, v43
	v_mul_f32_e32 v151, v45, v45
	v_fmac_f32_e32 v150, v42, v42
	v_fmac_f32_e32 v151, v44, v44
	v_add_f32_e32 v152, v150, v151
	v_add_f32_e32 v162, v162, v152
	v_cvt_pk_f16_f32 v174, v42, v43
	v_cvt_pk_f16_f32 v175, v44, v45
	v_mul_f32_e32 v150, v47, v47
	v_mul_f32_e32 v151, v49, v49
	v_fmac_f32_e32 v150, v46, v46
	v_fmac_f32_e32 v151, v48, v48
	v_add_f32_e32 v152, v150, v151
	v_add_f32_e32 v162, v162, v152
	v_cvt_pk_f16_f32 v176, v46, v47
	v_cvt_pk_f16_f32 v177, v48, v49
	global_store_dwordx2 v146, v[170:171], s[10:11]
	global_store_dwordx2 v146, v[172:173], s[10:11] offset:512
	global_store_dwordx2 v146, v[174:175], s[10:11] offset:1024
	global_store_dwordx2 v146, v[176:177], s[10:11] offset:1536
	v_mul_f32_e32 v150, v51, v51
	v_mul_f32_e32 v151, v53, v53
	v_fmac_f32_e32 v150, v50, v50
	v_fmac_f32_e32 v151, v52, v52
	v_add_f32_e32 v163, v150, v151
	v_cvt_pk_f16_f32 v178, v50, v51
	v_cvt_pk_f16_f32 v179, v52, v53
	v_mul_f32_e32 v150, v55, v55
	v_mul_f32_e32 v151, v57, v57
	v_fmac_f32_e32 v150, v54, v54
	v_fmac_f32_e32 v151, v56, v56
	v_add_f32_e32 v152, v150, v151
	v_add_f32_e32 v163, v163, v152
	v_cvt_pk_f16_f32 v180, v54, v55
	v_cvt_pk_f16_f32 v181, v56, v57
	v_mul_f32_e32 v150, v59, v59
	v_mul_f32_e32 v151, v61, v61
	v_fmac_f32_e32 v150, v58, v58
	v_fmac_f32_e32 v151, v60, v60
	v_add_f32_e32 v152, v150, v151
	v_add_f32_e32 v163, v163, v152
	v_cvt_pk_f16_f32 v182, v58, v59
	v_cvt_pk_f16_f32 v183, v60, v61
	v_mul_f32_e32 v150, v63, v63
	v_mul_f32_e32 v151, v65, v65
	v_fmac_f32_e32 v150, v62, v62
	v_fmac_f32_e32 v151, v64, v64
	v_add_f32_e32 v152, v150, v151
	v_add_f32_e32 v163, v163, v152
	v_cvt_pk_f16_f32 v184, v62, v63
	v_cvt_pk_f16_f32 v185, v64, v65
	global_store_dwordx2 v147, v[178:179], s[10:11]
	global_store_dwordx2 v147, v[180:181], s[10:11] offset:512
	global_store_dwordx2 v147, v[182:183], s[10:11] offset:1024
	global_store_dwordx2 v147, v[184:185], s[10:11] offset:1536
	ds_bpermute_b32 v164, v130, v160
	ds_bpermute_b32 v165, v130, v161
	ds_bpermute_b32 v166, v130, v162
	ds_bpermute_b32 v167, v130, v163
	s_waitcnt lgkmcnt(0)
	v_add_f32_e32 v160, v160, v164
	v_add_f32_e32 v161, v161, v165
	v_add_f32_e32 v162, v162, v166
	v_add_f32_e32 v163, v163, v167
	ds_bpermute_b32 v164, v131, v160
	ds_bpermute_b32 v165, v131, v161
	ds_bpermute_b32 v166, v131, v162
	ds_bpermute_b32 v167, v131, v163
	s_waitcnt lgkmcnt(0)
	v_add_f32_e32 v160, v160, v164
	v_add_f32_e32 v161, v161, v165
	v_add_f32_e32 v162, v162, v166
	v_add_f32_e32 v163, v163, v167
	ds_bpermute_b32 v164, v132, v160
	ds_bpermute_b32 v165, v132, v161
	ds_bpermute_b32 v166, v132, v162
	ds_bpermute_b32 v167, v132, v163
	s_waitcnt lgkmcnt(0)
	v_add_f32_e32 v160, v160, v164
	v_add_f32_e32 v161, v161, v165
	v_add_f32_e32 v162, v162, v166
	v_add_f32_e32 v163, v163, v167
	ds_bpermute_b32 v164, v133, v160
	ds_bpermute_b32 v165, v133, v161
	ds_bpermute_b32 v166, v133, v162
	ds_bpermute_b32 v167, v133, v163
	s_waitcnt lgkmcnt(0)
	v_add_f32_e32 v160, v160, v164
	v_add_f32_e32 v161, v161, v165
	v_add_f32_e32 v162, v162, v166
	v_add_f32_e32 v163, v163, v167
	ds_bpermute_b32 v164, v134, v160
	ds_bpermute_b32 v165, v134, v161
	ds_bpermute_b32 v166, v134, v162
	ds_bpermute_b32 v167, v134, v163
	s_waitcnt lgkmcnt(0)
	v_add_f32_e32 v160, v160, v164
	v_add_f32_e32 v161, v161, v165
	v_add_f32_e32 v162, v162, v166
	v_add_f32_e32 v163, v163, v167
	ds_bpermute_b32 v164, v135, v160
	ds_bpermute_b32 v165, v135, v161
	ds_bpermute_b32 v166, v135, v162
	ds_bpermute_b32 v167, v135, v163
	s_waitcnt lgkmcnt(0)
	v_add_f32_e32 v160, v160, v164
	v_add_f32_e32 v161, v161, v165
	v_add_f32_e32 v162, v162, v166
	v_add_f32_e32 v163, v163, v167
	v_cndmask_b32_e64 v164, 0, v160, s[12:13]
	v_cndmask_b32_e64 v165, 0, v161, s[12:13]
	v_cndmask_b32_e64 v166, 0, v162, s[12:13]
	v_cndmask_b32_e64 v167, 0, v163, s[12:13]
	s_mov_b64 exec, 0xffff
	global_store_dword v186, v164, s[6:7]
	global_store_dword v187, v165, s[6:7]
	global_store_dword v188, v166, s[6:7]
	global_store_dword v189, v167, s[6:7]
	s_mov_b64 exec, -1
	s_add_i32 s6, s3, 0x0
	s_lshl_b32 s6, s6, 12
	s_add_u32 s4, s18, s6
	s_addc_u32 s5, s19, 0
	global_load_dwordx4 v[2:5], v140, s[4:5] nt
	global_load_dwordx4 v[6:9], v140, s[4:5] offset:1024 nt
	global_load_dwordx4 v[10:13], v140, s[4:5] offset:2048 nt
	global_load_dwordx4 v[14:17], v140, s[4:5] offset:3072 nt
	global_load_dwordx4 v[18:21], v141, s[4:5] nt
	global_load_dwordx4 v[22:25], v141, s[4:5] offset:1024 nt
	global_load_dwordx4 v[26:29], v141, s[4:5] offset:2048 nt
	global_load_dwordx4 v[30:33], v141, s[4:5] offset:3072 nt
	global_load_dwordx4 v[34:37], v142, s[4:5] nt
	global_load_dwordx4 v[38:41], v142, s[4:5] offset:1024 nt
	global_load_dwordx4 v[42:45], v142, s[4:5] offset:2048 nt
	global_load_dwordx4 v[46:49], v142, s[4:5] offset:3072 nt
	global_load_dwordx4 v[50:53], v143, s[4:5] nt
	global_load_dwordx4 v[54:57], v143, s[4:5] offset:1024 nt
	global_load_dwordx4 v[58:61], v143, s[4:5] offset:2048 nt
	global_load_dwordx4 v[62:65], v143, s[4:5] offset:3072 nt
	s_waitcnt vmcnt(36)
; __device__ void p0_xconv(const Args& a) {
;     ...
;         for (int r = 0; r < 4; ++r) {
;             const int row = row0 + r * nwv;
;             if (row < MROWS) {
;                 float ss = 0.f;
; #pragma unroll
;                 for (int i = 0; i < 4; ++i) {
;                     const f32x4 x = v[r][i];
;                     ss += (x[0] * x[0] + x[1] * x[1]) + (x[2] * x[2] + x[3] * x[3]);
;                     f16x4 h; h[0] = (f16)x[0]; h[1] = (f16)x[1]; h[2] = (f16)x[2]; h[3] = (f16)x[3];
;                     *(f16x4*)(XH + (size_t)row * DM + i * 256 + lane * 4) = h;
;                 }
; #pragma unroll
;                 for (int o = 1; o < 64; o <<= 1) ss += __shfl_xor(ss, o);
;                 if (lane < 16) SS[(size_t)row * 16 + lane] = (lane == 0) ? ss : 0.f;
	s_add_i32 s6, s3, 0x3000
	s_lshl_b32 s7, s6, 11
	s_add_u32 s10, s40, s7
	s_addc_u32 s11, s41, 0
	s_lshl_b32 s7, s6, 6
	s_add_u32 s6, s40, s7
	s_addc_u32 s7, s41, 0
	s_add_u32 s6, s6, 0x1f800000
	s_addc_u32 s7, s7, 0
	v_mul_f32_e32 v150, v67, v67
	v_mul_f32_e32 v151, v69, v69
	v_fmac_f32_e32 v150, v66, v66
	v_fmac_f32_e32 v151, v68, v68
	v_add_f32_e32 v160, v150, v151
	v_cvt_pk_f16_f32 v170, v66, v67
	v_cvt_pk_f16_f32 v171, v68, v69
	v_mul_f32_e32 v150, v71, v71
	v_mul_f32_e32 v151, v73, v73
	v_fmac_f32_e32 v150, v70, v70
	v_fmac_f32_e32 v151, v72, v72
	v_add_f32_e32 v152, v150, v151
	v_add_f32_e32 v160, v160, v152
	v_cvt_pk_f16_f32 v172, v70, v71
	v_cvt_pk_f16_f32 v173, v72, v73
	v_mul_f32_e32 v150, v75, v75
	v_mul_f32_e32 v151, v77, v77
	v_fmac_f32_e32 v150, v74, v74
	v_fmac_f32_e32 v151, v76, v76
	v_add_f32_e32 v152, v150, v151
	v_add_f32_e32 v160, v160, v152
	v_cvt_pk_f16_f32 v174, v74, v75
	v_cvt_pk_f16_f32 v175, v76, v77
	v_mul_f32_e32 v150, v79, v79
	v_mul_f32_e32 v151, v81, v81
	v_fmac_f32_e32 v150, v78, v78
	v_fmac_f32_e32 v151, v80, v80
	v_add_f32_e32 v152, v150, v151
	v_add_f32_e32 v160, v160, v152
	v_cvt_pk_f16_f32 v176, v78, v79
	v_cvt_pk_f16_f32 v177, v80, v81
	global_store_dwordx2 v144, v[170:171], s[10:11]
	global_store_dwordx2 v144, v[172:173], s[10:11] offset:512
	global_store_dwordx2 v144, v[174:175], s[10:11] offset:1024
	global_store_dwordx2 v144, v[176:177], s[10:11] offset:1536
	v_mul_f32_e32 v150, v83, v83
	v_mul_f32_e32 v151, v85, v85
	v_fmac_f32_e32 v150, v82, v82
	v_fmac_f32_e32 v151, v84, v84
	v_add_f32_e32 v161, v150, v151
	v_cvt_pk_f16_f32 v178, v82, v83
	v_cvt_pk_f16_f32 v179, v84, v85
	v_mul_f32_e32 v150, v87, v87
	v_mul_f32_e32 v151, v89, v89
	v_fmac_f32_e32 v150, v86, v86
	v_fmac_f32_e32 v151, v88, v88
	v_add_f32_e32 v152, v150, v151
	v_add_f32_e32 v161, v161, v152
	v_cvt_pk_f16_f32 v180, v86, v87
	v_cvt_pk_f16_f32 v181, v88, v89
	v_mul_f32_e32 v150, v91, v91
	v_mul_f32_e32 v151, v93, v93
	v_fmac_f32_e32 v150, v90, v90
	v_fmac_f32_e32 v151, v92, v92
	v_add_f32_e32 v152, v150, v151
	v_add_f32_e32 v161, v161, v152
	v_cvt_pk_f16_f32 v182, v90, v91
	v_cvt_pk_f16_f32 v183, v92, v93
	v_mul_f32_e32 v150, v95, v95
	v_mul_f32_e32 v151, v97, v97
	v_fmac_f32_e32 v150, v94, v94
	v_fmac_f32_e32 v151, v96, v96
	v_add_f32_e32 v152, v150, v151
	v_add_f32_e32 v161, v161, v152
	v_cvt_pk_f16_f32 v184, v94, v95
	v_cvt_pk_f16_f32 v185, v96, v97
	global_store_dwordx2 v145, v[178:179], s[10:11]
	global_store_dwordx2 v145, v[180:181], s[10:11] offset:512
	global_store_dwordx2 v145, v[182:183], s[10:11] offset:1024
	global_store_dwordx2 v145, v[184:185], s[10:11] offset:1536
	v_mul_f32_e32 v150, v99, v99
	v_mul_f32_e32 v151, v101, v101
	v_fmac_f32_e32 v150, v98, v98
	v_fmac_f32_e32 v151, v100, v100
	v_add_f32_e32 v162, v150, v151
	v_cvt_pk_f16_f32 v170, v98, v99
	v_cvt_pk_f16_f32 v171, v100, v101
	v_mul_f32_e32 v150, v103, v103
	v_mul_f32_e32 v151, v105, v105
	v_fmac_f32_e32 v150, v102, v102
	v_fmac_f32_e32 v151, v104, v104
	v_add_f32_e32 v152, v150, v151
	v_add_f32_e32 v162, v162, v152
	v_cvt_pk_f16_f32 v172, v102, v103
	v_cvt_pk_f16_f32 v173, v104, v105
	v_mul_f32_e32 v150, v107, v107
	v_mul_f32_e32 v151, v109, v109
	v_fmac_f32_e32 v150, v106, v106
	v_fmac_f32_e32 v151, v108, v108
	v_add_f32_e32 v152, v150, v151
	v_add_f32_e32 v162, v162, v152
	v_cvt_pk_f16_f32 v174, v106, v107
	v_cvt_pk_f16_f32 v175, v108, v109
	v_mul_f32_e32 v150, v111, v111
	v_mul_f32_e32 v151, v113, v113
	v_fmac_f32_e32 v150, v110, v110
	v_fmac_f32_e32 v151, v112, v112
	v_add_f32_e32 v152, v150, v151
	v_add_f32_e32 v162, v162, v152
	v_cvt_pk_f16_f32 v176, v110, v111
	v_cvt_pk_f16_f32 v177, v112, v113
	global_store_dwordx2 v146, v[170:171], s[10:11]
	global_store_dwordx2 v146, v[172:173], s[10:11] offset:512
	global_store_dwordx2 v146, v[174:175], s[10:11] offset:1024
	global_store_dwordx2 v146, v[176:177], s[10:11] offset:1536
	v_mul_f32_e32 v150, v115, v115
	v_mul_f32_e32 v151, v117, v117
	v_fmac_f32_e32 v150, v114, v114
	v_fmac_f32_e32 v151, v116, v116
	v_add_f32_e32 v163, v150, v151
	v_cvt_pk_f16_f32 v178, v114, v115
	v_cvt_pk_f16_f32 v179, v116, v117
	v_mul_f32_e32 v150, v119, v119
	v_mul_f32_e32 v151, v121, v121
	v_fmac_f32_e32 v150, v118, v118
	v_fmac_f32_e32 v151, v120, v120
	v_add_f32_e32 v152, v150, v151
	v_add_f32_e32 v163, v163, v152
	v_cvt_pk_f16_f32 v180, v118, v119
	v_cvt_pk_f16_f32 v181, v120, v121
	v_mul_f32_e32 v150, v123, v123
	v_mul_f32_e32 v151, v125, v125
	v_fmac_f32_e32 v150, v122, v122
	v_fmac_f32_e32 v151, v124, v124
	v_add_f32_e32 v152, v150, v151
	v_add_f32_e32 v163, v163, v152
	v_cvt_pk_f16_f32 v182, v122, v123
	v_cvt_pk_f16_f32 v183, v124, v125
	v_mul_f32_e32 v150, v127, v127
	v_mul_f32_e32 v151, v129, v129
	v_fmac_f32_e32 v150, v126, v126
	v_fmac_f32_e32 v151, v128, v128
	v_add_f32_e32 v152, v150, v151
	v_add_f32_e32 v163, v163, v152
	v_cvt_pk_f16_f32 v184, v126, v127
	v_cvt_pk_f16_f32 v185, v128, v129
	global_store_dwordx2 v147, v[178:179], s[10:11]
	global_store_dwordx2 v147, v[180:181], s[10:11] offset:512
	global_store_dwordx2 v147, v[182:183], s[10:11] offset:1024
	global_store_dwordx2 v147, v[184:185], s[10:11] offset:1536
	ds_bpermute_b32 v164, v130, v160
	ds_bpermute_b32 v165, v130, v161
	ds_bpermute_b32 v166, v130, v162
	ds_bpermute_b32 v167, v130, v163
	s_waitcnt lgkmcnt(0)
	v_add_f32_e32 v160, v160, v164
	v_add_f32_e32 v161, v161, v165
	v_add_f32_e32 v162, v162, v166
	v_add_f32_e32 v163, v163, v167
	ds_bpermute_b32 v164, v131, v160
	ds_bpermute_b32 v165, v131, v161
	ds_bpermute_b32 v166, v131, v162
	ds_bpermute_b32 v167, v131, v163
	s_waitcnt lgkmcnt(0)
; __device__ void p0_xconv(const Args& a) {
;     ...
;         for (int r = 0; r < 4; ++r) {
;             const int row = row0 + r * nwv;
;             if (row < MROWS) {
;                 const float* src = (row < ROWS_PROMPT) ? a.x_prompt + (size_t)row * DM : a.x_sample + (size_t)(row - ROWS_PROMPT) * DM;
; #pragma unroll
;                 for (int i = 0; i < 4; ++i) v[r][i] = __builtin_nontemporal_load((const f32x4*)(src + i * 256 + lane * 4));
;     ...
;         for (int r = 0; r < 4; ++r) {
;             const int row = row0 + r * nwv;
;             if (row < MROWS) {
;                 float ss = 0.f;
; #pragma unroll
;                 for (int i = 0; i < 4; ++i) {
;                     const f32x4 x = v[r][i];
;                     ss += (x[0] * x[0] + x[1] * x[1]) + (x[2] * x[2] + x[3] * x[3]);
;                     f16x4 h; h[0] = (f16)x[0]; h[1] = (f16)x[1]; h[2] = (f16)x[2]; h[3] = (f16)x[3];
;                     *(f16x4*)(XH + (size_t)row * DM + i * 256 + lane * 4) = h;
;                 }
; #pragma unroll
;                 for (int o = 1; o < 64; o <<= 1) ss += __shfl_xor(ss, o);
;                 if (lane < 16) SS[(size_t)row * 16 + lane] = (lane == 0) ? ss : 0.f;
	v_add_f32_e32 v160, v160, v164
	v_add_f32_e32 v161, v161, v165
	v_add_f32_e32 v162, v162, v166
	v_add_f32_e32 v163, v163, v167
	ds_bpermute_b32 v164, v132, v160
	ds_bpermute_b32 v165, v132, v161
	ds_bpermute_b32 v166, v132, v162
	ds_bpermute_b32 v167, v132, v163
	s_waitcnt lgkmcnt(0)
	v_add_f32_e32 v160, v160, v164
	v_add_f32_e32 v161, v161, v165
	v_add_f32_e32 v162, v162, v166
	v_add_f32_e32 v163, v163, v167
	ds_bpermute_b32 v164, v133, v160
	ds_bpermute_b32 v165, v133, v161
	ds_bpermute_b32 v166, v133, v162
	ds_bpermute_b32 v167, v133, v163
	s_waitcnt lgkmcnt(0)
	v_add_f32_e32 v160, v160, v164
	v_add_f32_e32 v161, v161, v165
	v_add_f32_e32 v162, v162, v166
	v_add_f32_e32 v163, v163, v167
	ds_bpermute_b32 v164, v134, v160
	ds_bpermute_b32 v165, v134, v161
	ds_bpermute_b32 v166, v134, v162
	ds_bpermute_b32 v167, v134, v163
	s_waitcnt lgkmcnt(0)
	v_add_f32_e32 v160, v160, v164
	v_add_f32_e32 v161, v161, v165
	v_add_f32_e32 v162, v162, v166
	v_add_f32_e32 v163, v163, v167
	ds_bpermute_b32 v164, v135, v160
	ds_bpermute_b32 v165, v135, v161
	ds_bpermute_b32 v166, v135, v162
	ds_bpermute_b32 v167, v135, v163
	s_waitcnt lgkmcnt(0)
	v_add_f32_e32 v160, v160, v164
	v_add_f32_e32 v161, v161, v165
	v_add_f32_e32 v162, v162, v166
	v_add_f32_e32 v163, v163, v167
	v_cndmask_b32_e64 v164, 0, v160, s[12:13]
	v_cndmask_b32_e64 v165, 0, v161, s[12:13]
	v_cndmask_b32_e64 v166, 0, v162, s[12:13]
	v_cndmask_b32_e64 v167, 0, v163, s[12:13]
	s_mov_b64 exec, 0xffff
	global_store_dword v186, v164, s[6:7]
	global_store_dword v187, v165, s[6:7]
	global_store_dword v188, v166, s[6:7]
	global_store_dword v189, v167, s[6:7]
	s_mov_b64 exec, -1
	s_add_i32 s6, s3, 0x1000
	s_lshl_b32 s6, s6, 12
	s_add_u32 s4, s18, s6
	s_addc_u32 s5, s19, 0
	global_load_dwordx4 v[66:69], v140, s[4:5] nt
	global_load_dwordx4 v[70:73], v140, s[4:5] offset:1024 nt
	global_load_dwordx4 v[74:77], v140, s[4:5] offset:2048 nt
	global_load_dwordx4 v[78:81], v140, s[4:5] offset:3072 nt
	global_load_dwordx4 v[82:85], v141, s[4:5] nt
	global_load_dwordx4 v[86:89], v141, s[4:5] offset:1024 nt
	global_load_dwordx4 v[90:93], v141, s[4:5] offset:2048 nt
	global_load_dwordx4 v[94:97], v141, s[4:5] offset:3072 nt
	global_load_dwordx4 v[98:101], v142, s[4:5] nt
	global_load_dwordx4 v[102:105], v142, s[4:5] offset:1024 nt
	global_load_dwordx4 v[106:109], v142, s[4:5] offset:2048 nt
	global_load_dwordx4 v[110:113], v142, s[4:5] offset:3072 nt
	global_load_dwordx4 v[114:117], v143, s[4:5] nt
	global_load_dwordx4 v[118:121], v143, s[4:5] offset:1024 nt
	global_load_dwordx4 v[122:125], v143, s[4:5] offset:2048 nt
	global_load_dwordx4 v[126:129], v143, s[4:5] offset:3072 nt
	s_waitcnt vmcnt(36)
	s_add_i32 s6, s3, 0x4000
	s_lshl_b32 s7, s6, 11
	s_add_u32 s10, s40, s7
	s_addc_u32 s11, s41, 0
	s_lshl_b32 s7, s6, 6
	s_add_u32 s6, s40, s7
	s_addc_u32 s7, s41, 0
	s_add_u32 s6, s6, 0x1f800000
	s_addc_u32 s7, s7, 0
	v_mul_f32_e32 v150, v3, v3
	v_mul_f32_e32 v151, v5, v5
	v_fmac_f32_e32 v150, v2, v2
	v_fmac_f32_e32 v151, v4, v4
	v_add_f32_e32 v160, v150, v151
	v_cvt_pk_f16_f32 v170, v2, v3
	v_cvt_pk_f16_f32 v171, v4, v5
	v_mul_f32_e32 v150, v7, v7
	v_mul_f32_e32 v151, v9, v9
	v_fmac_f32_e32 v150, v6, v6
	v_fmac_f32_e32 v151, v8, v8
	v_add_f32_e32 v152, v150, v151
	v_add_f32_e32 v160, v160, v152
	v_cvt_pk_f16_f32 v172, v6, v7
	v_cvt_pk_f16_f32 v173, v8, v9
	v_mul_f32_e32 v150, v11, v11
	v_mul_f32_e32 v151, v13, v13
	v_fmac_f32_e32 v150, v10, v10
	v_fmac_f32_e32 v151, v12, v12
	v_add_f32_e32 v152, v150, v151
	v_add_f32_e32 v160, v160, v152
	v_cvt_pk_f16_f32 v174, v10, v11
	v_cvt_pk_f16_f32 v175, v12, v13
	v_mul_f32_e32 v150, v15, v15
	v_mul_f32_e32 v151, v17, v17
	v_fmac_f32_e32 v150, v14, v14
	v_fmac_f32_e32 v151, v16, v16
	v_add_f32_e32 v152, v150, v151
	v_add_f32_e32 v160, v160, v152
	v_cvt_pk_f16_f32 v176, v14, v15
	v_cvt_pk_f16_f32 v177, v16, v17
	global_store_dwordx2 v144, v[170:171], s[10:11]
	global_store_dwordx2 v144, v[172:173], s[10:11] offset:512
	global_store_dwordx2 v144, v[174:175], s[10:11] offset:1024
	global_store_dwordx2 v144, v[176:177], s[10:11] offset:1536
	v_mul_f32_e32 v150, v19, v19
	v_mul_f32_e32 v151, v21, v21
	v_fmac_f32_e32 v150, v18, v18
	v_fmac_f32_e32 v151, v20, v20
	v_add_f32_e32 v161, v150, v151
	v_cvt_pk_f16_f32 v178, v18, v19
	v_cvt_pk_f16_f32 v179, v20, v21
	v_mul_f32_e32 v150, v23, v23
	v_mul_f32_e32 v151, v25, v25
	v_fmac_f32_e32 v150, v22, v22
	v_fmac_f32_e32 v151, v24, v24
	v_add_f32_e32 v152, v150, v151
	v_add_f32_e32 v161, v161, v152
	v_cvt_pk_f16_f32 v180, v22, v23
	v_cvt_pk_f16_f32 v181, v24, v25
	v_mul_f32_e32 v150, v27, v27
	v_mul_f32_e32 v151, v29, v29
	v_fmac_f32_e32 v150, v26, v26
	v_fmac_f32_e32 v151, v28, v28
	v_add_f32_e32 v152, v150, v151
	v_add_f32_e32 v161, v161, v152
	v_cvt_pk_f16_f32 v182, v26, v27
	v_cvt_pk_f16_f32 v183, v28, v29
	v_mul_f32_e32 v150, v31, v31
	v_mul_f32_e32 v151, v33, v33
	v_fmac_f32_e32 v150, v30, v30
	v_fmac_f32_e32 v151, v32, v32
	v_add_f32_e32 v152, v150, v151
	v_add_f32_e32 v161, v161, v152
	v_cvt_pk_f16_f32 v184, v30, v31
	v_cvt_pk_f16_f32 v185, v32, v33
	global_store_dwordx2 v145, v[178:179], s[10:11]
	global_store_dwordx2 v145, v[180:181], s[10:11] offset:512
	global_store_dwordx2 v145, v[182:183], s[10:11] offset:1024
	global_store_dwordx2 v145, v[184:185], s[10:11] offset:1536
	v_mul_f32_e32 v150, v35, v35
	v_mul_f32_e32 v151, v37, v37
	v_fmac_f32_e32 v150, v34, v34
	v_fmac_f32_e32 v151, v36, v36
	v_add_f32_e32 v162, v150, v151
	v_cvt_pk_f16_f32 v170, v34, v35
	v_cvt_pk_f16_f32 v171, v36, v37
	v_mul_f32_e32 v150, v39, v39
	v_mul_f32_e32 v151, v41, v41
	v_fmac_f32_e32 v150, v38, v38
	v_fmac_f32_e32 v151, v40, v40
	v_add_f32_e32 v152, v150, v151
; __device__ void p0_xconv(const Args& a) {
;     ...
;         for (int r = 0; r < 4; ++r) {
;             const int row = row0 + r * nwv;
;             if (row < MROWS) {
;                 const float* src = (row < ROWS_PROMPT) ? a.x_prompt + (size_t)row * DM : a.x_sample + (size_t)(row - ROWS_PROMPT) * DM;
; #pragma unroll
;                 for (int i = 0; i < 4; ++i) v[r][i] = __builtin_nontemporal_load((const f32x4*)(src + i * 256 + lane * 4));
;     ...
;         for (int r = 0; r < 4; ++r) {
;             const int row = row0 + r * nwv;
;             if (row < MROWS) {
;                 float ss = 0.f;
; #pragma unroll
;                 for (int i = 0; i < 4; ++i) {
;                     const f32x4 x = v[r][i];
;                     ss += (x[0] * x[0] + x[1] * x[1]) + (x[2] * x[2] + x[3] * x[3]);
;                     f16x4 h; h[0] = (f16)x[0]; h[1] = (f16)x[1]; h[2] = (f16)x[2]; h[3] = (f16)x[3];
;                     *(f16x4*)(XH + (size_t)row * DM + i * 256 + lane * 4) = h;
;                 }
; #pragma unroll
;                 for (int o = 1; o < 64; o <<= 1) ss += __shfl_xor(ss, o);
;                 if (lane < 16) SS[(size_t)row * 16 + lane] = (lane == 0) ? ss : 0.f;
	v_add_f32_e32 v162, v162, v152
	v_cvt_pk_f16_f32 v172, v38, v39
	v_cvt_pk_f16_f32 v173, v40, v41
	v_mul_f32_e32 v150, v43, v43
	v_mul_f32_e32 v151, v45, v45
	v_fmac_f32_e32 v150, v42, v42
	v_fmac_f32_e32 v151, v44, v44
	v_add_f32_e32 v152, v150, v151
	v_add_f32_e32 v162, v162, v152
	v_cvt_pk_f16_f32 v174, v42, v43
	v_cvt_pk_f16_f32 v175, v44, v45
	v_mul_f32_e32 v150, v47, v47
	v_mul_f32_e32 v151, v49, v49
	v_fmac_f32_e32 v150, v46, v46
	v_fmac_f32_e32 v151, v48, v48
	v_add_f32_e32 v152, v150, v151
	v_add_f32_e32 v162, v162, v152
	v_cvt_pk_f16_f32 v176, v46, v47
	v_cvt_pk_f16_f32 v177, v48, v49
	global_store_dwordx2 v146, v[170:171], s[10:11]
	global_store_dwordx2 v146, v[172:173], s[10:11] offset:512
	global_store_dwordx2 v146, v[174:175], s[10:11] offset:1024
	global_store_dwordx2 v146, v[176:177], s[10:11] offset:1536
	v_mul_f32_e32 v150, v51, v51
	v_mul_f32_e32 v151, v53, v53
	v_fmac_f32_e32 v150, v50, v50
	v_fmac_f32_e32 v151, v52, v52
	v_add_f32_e32 v163, v150, v151
	v_cvt_pk_f16_f32 v178, v50, v51
	v_cvt_pk_f16_f32 v179, v52, v53
	v_mul_f32_e32 v150, v55, v55
	v_mul_f32_e32 v151, v57, v57
	v_fmac_f32_e32 v150, v54, v54
	v_fmac_f32_e32 v151, v56, v56
	v_add_f32_e32 v152, v150, v151
	v_add_f32_e32 v163, v163, v152
	v_cvt_pk_f16_f32 v180, v54, v55
	v_cvt_pk_f16_f32 v181, v56, v57
	v_mul_f32_e32 v150, v59, v59
	v_mul_f32_e32 v151, v61, v61
	v_fmac_f32_e32 v150, v58, v58
	v_fmac_f32_e32 v151, v60, v60
	v_add_f32_e32 v152, v150, v151
	v_add_f32_e32 v163, v163, v152
	v_cvt_pk_f16_f32 v182, v58, v59
	v_cvt_pk_f16_f32 v183, v60, v61
	v_mul_f32_e32 v150, v63, v63
	v_mul_f32_e32 v151, v65, v65
	v_fmac_f32_e32 v150, v62, v62
	v_fmac_f32_e32 v151, v64, v64
	v_add_f32_e32 v152, v150, v151
	v_add_f32_e32 v163, v163, v152
	v_cvt_pk_f16_f32 v184, v62, v63
	v_cvt_pk_f16_f32 v185, v64, v65
	global_store_dwordx2 v147, v[178:179], s[10:11]
	global_store_dwordx2 v147, v[180:181], s[10:11] offset:512
	global_store_dwordx2 v147, v[182:183], s[10:11] offset:1024
	global_store_dwordx2 v147, v[184:185], s[10:11] offset:1536
	ds_bpermute_b32 v164, v130, v160
	ds_bpermute_b32 v165, v130, v161
	ds_bpermute_b32 v166, v130, v162
	ds_bpermute_b32 v167, v130, v163
	s_waitcnt lgkmcnt(0)
	v_add_f32_e32 v160, v160, v164
	v_add_f32_e32 v161, v161, v165
	v_add_f32_e32 v162, v162, v166
	v_add_f32_e32 v163, v163, v167
	ds_bpermute_b32 v164, v131, v160
	ds_bpermute_b32 v165, v131, v161
	ds_bpermute_b32 v166, v131, v162
	ds_bpermute_b32 v167, v131, v163
	s_waitcnt lgkmcnt(0)
	v_add_f32_e32 v160, v160, v164
	v_add_f32_e32 v161, v161, v165
	v_add_f32_e32 v162, v162, v166
	v_add_f32_e32 v163, v163, v167
	ds_bpermute_b32 v164, v132, v160
	ds_bpermute_b32 v165, v132, v161
	ds_bpermute_b32 v166, v132, v162
	ds_bpermute_b32 v167, v132, v163
	s_waitcnt lgkmcnt(0)
	v_add_f32_e32 v160, v160, v164
	v_add_f32_e32 v161, v161, v165
	v_add_f32_e32 v162, v162, v166
	v_add_f32_e32 v163, v163, v167
	ds_bpermute_b32 v164, v133, v160
	ds_bpermute_b32 v165, v133, v161
	ds_bpermute_b32 v166, v133, v162
	ds_bpermute_b32 v167, v133, v163
	s_waitcnt lgkmcnt(0)
	v_add_f32_e32 v160, v160, v164
	v_add_f32_e32 v161, v161, v165
	v_add_f32_e32 v162, v162, v166
	v_add_f32_e32 v163, v163, v167
	ds_bpermute_b32 v164, v134, v160
	ds_bpermute_b32 v165, v134, v161
	ds_bpermute_b32 v166, v134, v162
	ds_bpermute_b32 v167, v134, v163
	s_waitcnt lgkmcnt(0)
	v_add_f32_e32 v160, v160, v164
	v_add_f32_e32 v161, v161, v165
	v_add_f32_e32 v162, v162, v166
	v_add_f32_e32 v163, v163, v167
	ds_bpermute_b32 v164, v135, v160
	ds_bpermute_b32 v165, v135, v161
	ds_bpermute_b32 v166, v135, v162
	ds_bpermute_b32 v167, v135, v163
	s_waitcnt lgkmcnt(0)
	v_add_f32_e32 v160, v160, v164
	v_add_f32_e32 v161, v161, v165
	v_add_f32_e32 v162, v162, v166
	v_add_f32_e32 v163, v163, v167
	v_cndmask_b32_e64 v164, 0, v160, s[12:13]
	v_cndmask_b32_e64 v165, 0, v161, s[12:13]
	v_cndmask_b32_e64 v166, 0, v162, s[12:13]
	v_cndmask_b32_e64 v167, 0, v163, s[12:13]
	s_mov_b64 exec, 0xffff
	global_store_dword v186, v164, s[6:7]
	global_store_dword v187, v165, s[6:7]
	global_store_dword v188, v166, s[6:7]
	global_store_dword v189, v167, s[6:7]
	s_mov_b64 exec, -1
	s_add_i32 s6, s3, 0x2000
	s_lshl_b32 s6, s6, 12
	s_add_u32 s4, s18, s6
	s_addc_u32 s5, s19, 0
	global_load_dwordx4 v[2:5], v140, s[4:5] nt
	global_load_dwordx4 v[6:9], v140, s[4:5] offset:1024 nt
	global_load_dwordx4 v[10:13], v140, s[4:5] offset:2048 nt
	global_load_dwordx4 v[14:17], v140, s[4:5] offset:3072 nt
	global_load_dwordx4 v[18:21], v141, s[4:5] nt
	global_load_dwordx4 v[22:25], v141, s[4:5] offset:1024 nt
	global_load_dwordx4 v[26:29], v141, s[4:5] offset:2048 nt
	global_load_dwordx4 v[30:33], v141, s[4:5] offset:3072 nt
	global_load_dwordx4 v[34:37], v142, s[4:5] nt
	global_load_dwordx4 v[38:41], v142, s[4:5] offset:1024 nt
	global_load_dwordx4 v[42:45], v142, s[4:5] offset:2048 nt
	global_load_dwordx4 v[46:49], v142, s[4:5] offset:3072 nt
	global_load_dwordx4 v[50:53], v143, s[4:5] nt
	global_load_dwordx4 v[54:57], v143, s[4:5] offset:1024 nt
	global_load_dwordx4 v[58:61], v143, s[4:5] offset:2048 nt
	global_load_dwordx4 v[62:65], v143, s[4:5] offset:3072 nt
	s_waitcnt vmcnt(36)
; __device__ void p0_xconv(const Args& a) {
;     ...
;         for (int r = 0; r < 4; ++r) {
;             const int row = row0 + r * nwv;
;             if (row < MROWS) {
;                 float ss = 0.f;
; #pragma unroll
;                 for (int i = 0; i < 4; ++i) {
;                     const f32x4 x = v[r][i];
;                     ss += (x[0] * x[0] + x[1] * x[1]) + (x[2] * x[2] + x[3] * x[3]);
;                     f16x4 h; h[0] = (f16)x[0]; h[1] = (f16)x[1]; h[2] = (f16)x[2]; h[3] = (f16)x[3];
;                     *(f16x4*)(XH + (size_t)row * DM + i * 256 + lane * 4) = h;
;                 }
; #pragma unroll
;                 for (int o = 1; o < 64; o <<= 1) ss += __shfl_xor(ss, o);
;                 if (lane < 16) SS[(size_t)row * 16 + lane] = (lane == 0) ? ss : 0.f;
	s_add_i32 s6, s3, 0x5000
	s_lshl_b32 s7, s6, 11
	s_add_u32 s10, s40, s7
	s_addc_u32 s11, s41, 0
	s_lshl_b32 s7, s6, 6
	s_add_u32 s6, s40, s7
	s_addc_u32 s7, s41, 0
	s_add_u32 s6, s6, 0x1f800000
	s_addc_u32 s7, s7, 0
	v_mul_f32_e32 v150, v67, v67
	v_mul_f32_e32 v151, v69, v69
	v_fmac_f32_e32 v150, v66, v66
	v_fmac_f32_e32 v151, v68, v68
	v_add_f32_e32 v160, v150, v151
	v_cvt_pk_f16_f32 v170, v66, v67
	v_cvt_pk_f16_f32 v171, v68, v69
	v_mul_f32_e32 v150, v71, v71
	v_mul_f32_e32 v151, v73, v73
	v_fmac_f32_e32 v150, v70, v70
	v_fmac_f32_e32 v151, v72, v72
	v_add_f32_e32 v152, v150, v151
	v_add_f32_e32 v160, v160, v152
	v_cvt_pk_f16_f32 v172, v70, v71
	v_cvt_pk_f16_f32 v173, v72, v73
	v_mul_f32_e32 v150, v75, v75
	v_mul_f32_e32 v151, v77, v77
	v_fmac_f32_e32 v150, v74, v74
	v_fmac_f32_e32 v151, v76, v76
	v_add_f32_e32 v152, v150, v151
	v_add_f32_e32 v160, v160, v152
	v_cvt_pk_f16_f32 v174, v74, v75
	v_cvt_pk_f16_f32 v175, v76, v77
	v_mul_f32_e32 v150, v79, v79
	v_mul_f32_e32 v151, v81, v81
	v_fmac_f32_e32 v150, v78, v78
	v_fmac_f32_e32 v151, v80, v80
	v_add_f32_e32 v152, v150, v151
	v_add_f32_e32 v160, v160, v152
	v_cvt_pk_f16_f32 v176, v78, v79
	v_cvt_pk_f16_f32 v177, v80, v81
	global_store_dwordx2 v144, v[170:171], s[10:11]
	global_store_dwordx2 v144, v[172:173], s[10:11] offset:512
	global_store_dwordx2 v144, v[174:175], s[10:11] offset:1024
	global_store_dwordx2 v144, v[176:177], s[10:11] offset:1536
	v_mul_f32_e32 v150, v83, v83
	v_mul_f32_e32 v151, v85, v85
	v_fmac_f32_e32 v150, v82, v82
	v_fmac_f32_e32 v151, v84, v84
	v_add_f32_e32 v161, v150, v151
	v_cvt_pk_f16_f32 v178, v82, v83
	v_cvt_pk_f16_f32 v179, v84, v85
	v_mul_f32_e32 v150, v87, v87
	v_mul_f32_e32 v151, v89, v89
	v_fmac_f32_e32 v150, v86, v86
	v_fmac_f32_e32 v151, v88, v88
	v_add_f32_e32 v152, v150, v151
	v_add_f32_e32 v161, v161, v152
	v_cvt_pk_f16_f32 v180, v86, v87
	v_cvt_pk_f16_f32 v181, v88, v89
	v_mul_f32_e32 v150, v91, v91
	v_mul_f32_e32 v151, v93, v93
	v_fmac_f32_e32 v150, v90, v90
	v_fmac_f32_e32 v151, v92, v92
	v_add_f32_e32 v152, v150, v151
	v_add_f32_e32 v161, v161, v152
	v_cvt_pk_f16_f32 v182, v90, v91
	v_cvt_pk_f16_f32 v183, v92, v93
	v_mul_f32_e32 v150, v95, v95
	v_mul_f32_e32 v151, v97, v97
	v_fmac_f32_e32 v150, v94, v94
	v_fmac_f32_e32 v151, v96, v96
	v_add_f32_e32 v152, v150, v151
	v_add_f32_e32 v161, v161, v152
	v_cvt_pk_f16_f32 v184, v94, v95
	v_cvt_pk_f16_f32 v185, v96, v97
	global_store_dwordx2 v145, v[178:179], s[10:11]
	global_store_dwordx2 v145, v[180:181], s[10:11] offset:512
	global_store_dwordx2 v145, v[182:183], s[10:11] offset:1024
	global_store_dwordx2 v145, v[184:185], s[10:11] offset:1536
	v_mul_f32_e32 v150, v99, v99
	v_mul_f32_e32 v151, v101, v101
	v_fmac_f32_e32 v150, v98, v98
	v_fmac_f32_e32 v151, v100, v100
	v_add_f32_e32 v162, v150, v151
	v_cvt_pk_f16_f32 v170, v98, v99
	v_cvt_pk_f16_f32 v171, v100, v101
	v_mul_f32_e32 v150, v103, v103
	v_mul_f32_e32 v151, v105, v105
	v_fmac_f32_e32 v150, v102, v102
	v_fmac_f32_e32 v151, v104, v104
	v_add_f32_e32 v152, v150, v151
	v_add_f32_e32 v162, v162, v152
	v_cvt_pk_f16_f32 v172, v102, v103
	v_cvt_pk_f16_f32 v173, v104, v105
	v_mul_f32_e32 v150, v107, v107
	v_mul_f32_e32 v151, v109, v109
	v_fmac_f32_e32 v150, v106, v106
	v_fmac_f32_e32 v151, v108, v108
	v_add_f32_e32 v152, v150, v151
	v_add_f32_e32 v162, v162, v152
	v_cvt_pk_f16_f32 v174, v106, v107
	v_cvt_pk_f16_f32 v175, v108, v109
	v_mul_f32_e32 v150, v111, v111
	v_mul_f32_e32 v151, v113, v113
	v_fmac_f32_e32 v150, v110, v110
	v_fmac_f32_e32 v151, v112, v112
	v_add_f32_e32 v152, v150, v151
	v_add_f32_e32 v162, v162, v152
	v_cvt_pk_f16_f32 v176, v110, v111
	v_cvt_pk_f16_f32 v177, v112, v113
	global_store_dwordx2 v146, v[170:171], s[10:11]
	global_store_dwordx2 v146, v[172:173], s[10:11] offset:512
	global_store_dwordx2 v146, v[174:175], s[10:11] offset:1024
	global_store_dwordx2 v146, v[176:177], s[10:11] offset:1536
	v_mul_f32_e32 v150, v115, v115
	v_mul_f32_e32 v151, v117, v117
	v_fmac_f32_e32 v150, v114, v114
	v_fmac_f32_e32 v151, v116, v116
	v_add_f32_e32 v163, v150, v151
	v_cvt_pk_f16_f32 v178, v114, v115
	v_cvt_pk_f16_f32 v179, v116, v117
	v_mul_f32_e32 v150, v119, v119
	v_mul_f32_e32 v151, v121, v121
	v_fmac_f32_e32 v150, v118, v118
	v_fmac_f32_e32 v151, v120, v120
	v_add_f32_e32 v152, v150, v151
	v_add_f32_e32 v163, v163, v152
	v_cvt_pk_f16_f32 v180, v118, v119
	v_cvt_pk_f16_f32 v181, v120, v121
	v_mul_f32_e32 v150, v123, v123
	v_mul_f32_e32 v151, v125, v125
	v_fmac_f32_e32 v150, v122, v122
	v_fmac_f32_e32 v151, v124, v124
	v_add_f32_e32 v152, v150, v151
	v_add_f32_e32 v163, v163, v152
	v_cvt_pk_f16_f32 v182, v122, v123
	v_cvt_pk_f16_f32 v183, v124, v125
	v_mul_f32_e32 v150, v127, v127
	v_mul_f32_e32 v151, v129, v129
	v_fmac_f32_e32 v150, v126, v126
	v_fmac_f32_e32 v151, v128, v128
	v_add_f32_e32 v152, v150, v151
	v_add_f32_e32 v163, v163, v152
	v_cvt_pk_f16_f32 v184, v126, v127
	v_cvt_pk_f16_f32 v185, v128, v129
	global_store_dwordx2 v147, v[178:179], s[10:11]
	global_store_dwordx2 v147, v[180:181], s[10:11] offset:512
	global_store_dwordx2 v147, v[182:183], s[10:11] offset:1024
	global_store_dwordx2 v147, v[184:185], s[10:11] offset:1536
	ds_bpermute_b32 v164, v130, v160
	ds_bpermute_b32 v165, v130, v161
	ds_bpermute_b32 v166, v130, v162
	ds_bpermute_b32 v167, v130, v163
	s_waitcnt lgkmcnt(0)
	v_add_f32_e32 v160, v160, v164
	v_add_f32_e32 v161, v161, v165
	v_add_f32_e32 v162, v162, v166
	v_add_f32_e32 v163, v163, v167
	ds_bpermute_b32 v164, v131, v160
	ds_bpermute_b32 v165, v131, v161
	ds_bpermute_b32 v166, v131, v162
	ds_bpermute_b32 v167, v131, v163
	s_waitcnt lgkmcnt(0)
; __device__ void p0_xconv(const Args& a) {
;     ...
;         for (int r = 0; r < 4; ++r) {
;             const int row = row0 + r * nwv;
;             if (row < MROWS) {
;                 const float* src = (row < ROWS_PROMPT) ? a.x_prompt + (size_t)row * DM : a.x_sample + (size_t)(row - ROWS_PROMPT) * DM;
; #pragma unroll
;                 for (int i = 0; i < 4; ++i) v[r][i] = __builtin_nontemporal_load((const f32x4*)(src + i * 256 + lane * 4));
;     ...
;         for (int r = 0; r < 4; ++r) {
;             const int row = row0 + r * nwv;
;             if (row < MROWS) {
;                 float ss = 0.f;
; #pragma unroll
;                 for (int i = 0; i < 4; ++i) {
;                     const f32x4 x = v[r][i];
;                     ss += (x[0] * x[0] + x[1] * x[1]) + (x[2] * x[2] + x[3] * x[3]);
;                     f16x4 h; h[0] = (f16)x[0]; h[1] = (f16)x[1]; h[2] = (f16)x[2]; h[3] = (f16)x[3];
;                     *(f16x4*)(XH + (size_t)row * DM + i * 256 + lane * 4) = h;
;                 }
; #pragma unroll
;                 for (int o = 1; o < 64; o <<= 1) ss += __shfl_xor(ss, o);
;                 if (lane < 16) SS[(size_t)row * 16 + lane] = (lane == 0) ? ss : 0.f;
	v_add_f32_e32 v160, v160, v164
	v_add_f32_e32 v161, v161, v165
	v_add_f32_e32 v162, v162, v166
	v_add_f32_e32 v163, v163, v167
	ds_bpermute_b32 v164, v132, v160
	ds_bpermute_b32 v165, v132, v161
	ds_bpermute_b32 v166, v132, v162
	ds_bpermute_b32 v167, v132, v163
	s_waitcnt lgkmcnt(0)
	v_add_f32_e32 v160, v160, v164
	v_add_f32_e32 v161, v161, v165
	v_add_f32_e32 v162, v162, v166
	v_add_f32_e32 v163, v163, v167
	ds_bpermute_b32 v164, v133, v160
	ds_bpermute_b32 v165, v133, v161
	ds_bpermute_b32 v166, v133, v162
	ds_bpermute_b32 v167, v133, v163
	s_waitcnt lgkmcnt(0)
	v_add_f32_e32 v160, v160, v164
	v_add_f32_e32 v161, v161, v165
	v_add_f32_e32 v162, v162, v166
	v_add_f32_e32 v163, v163, v167
	ds_bpermute_b32 v164, v134, v160
	ds_bpermute_b32 v165, v134, v161
	ds_bpermute_b32 v166, v134, v162
	ds_bpermute_b32 v167, v134, v163
	s_waitcnt lgkmcnt(0)
	v_add_f32_e32 v160, v160, v164
	v_add_f32_e32 v161, v161, v165
	v_add_f32_e32 v162, v162, v166
	v_add_f32_e32 v163, v163, v167
	ds_bpermute_b32 v164, v135, v160
	ds_bpermute_b32 v165, v135, v161
	ds_bpermute_b32 v166, v135, v162
	ds_bpermute_b32 v167, v135, v163
	s_waitcnt lgkmcnt(0)
	v_add_f32_e32 v160, v160, v164
	v_add_f32_e32 v161, v161, v165
	v_add_f32_e32 v162, v162, v166
	v_add_f32_e32 v163, v163, v167
	v_cndmask_b32_e64 v164, 0, v160, s[12:13]
	v_cndmask_b32_e64 v165, 0, v161, s[12:13]
	v_cndmask_b32_e64 v166, 0, v162, s[12:13]
	v_cndmask_b32_e64 v167, 0, v163, s[12:13]
	s_mov_b64 exec, 0xffff
	global_store_dword v186, v164, s[6:7]
	global_store_dword v187, v165, s[6:7]
	global_store_dword v188, v166, s[6:7]
	global_store_dword v189, v167, s[6:7]
	s_mov_b64 exec, -1
	s_add_i32 s6, s3, 0x3000
	s_lshl_b32 s6, s6, 12
	s_add_u32 s4, s18, s6
	s_addc_u32 s5, s19, 0
	global_load_dwordx4 v[66:69], v140, s[4:5] nt
	global_load_dwordx4 v[70:73], v140, s[4:5] offset:1024 nt
	global_load_dwordx4 v[74:77], v140, s[4:5] offset:2048 nt
	global_load_dwordx4 v[78:81], v140, s[4:5] offset:3072 nt
	global_load_dwordx4 v[82:85], v141, s[4:5] nt
	global_load_dwordx4 v[86:89], v141, s[4:5] offset:1024 nt
	global_load_dwordx4 v[90:93], v141, s[4:5] offset:2048 nt
	global_load_dwordx4 v[94:97], v141, s[4:5] offset:3072 nt
	global_load_dwordx4 v[98:101], v142, s[4:5] nt
	global_load_dwordx4 v[102:105], v142, s[4:5] offset:1024 nt
	global_load_dwordx4 v[106:109], v142, s[4:5] offset:2048 nt
	global_load_dwordx4 v[110:113], v142, s[4:5] offset:3072 nt
	global_load_dwordx4 v[114:117], v143, s[4:5] nt
	global_load_dwordx4 v[118:121], v143, s[4:5] offset:1024 nt
	global_load_dwordx4 v[122:125], v143, s[4:5] offset:2048 nt
	global_load_dwordx4 v[126:129], v143, s[4:5] offset:3072 nt
	s_waitcnt vmcnt(36)
	s_add_i32 s6, s3, 0x6000
	s_lshl_b32 s7, s6, 11
	s_add_u32 s10, s40, s7
	s_addc_u32 s11, s41, 0
	s_lshl_b32 s7, s6, 6
	s_add_u32 s6, s40, s7
	s_addc_u32 s7, s41, 0
	s_add_u32 s6, s6, 0x1f800000
	s_addc_u32 s7, s7, 0
	v_mul_f32_e32 v150, v3, v3
	v_mul_f32_e32 v151, v5, v5
	v_fmac_f32_e32 v150, v2, v2
	v_fmac_f32_e32 v151, v4, v4
	v_add_f32_e32 v160, v150, v151
	v_cvt_pk_f16_f32 v170, v2, v3
	v_cvt_pk_f16_f32 v171, v4, v5
	v_mul_f32_e32 v150, v7, v7
	v_mul_f32_e32 v151, v9, v9
	v_fmac_f32_e32 v150, v6, v6
	v_fmac_f32_e32 v151, v8, v8
	v_add_f32_e32 v152, v150, v151
	v_add_f32_e32 v160, v160, v152
	v_cvt_pk_f16_f32 v172, v6, v7
	v_cvt_pk_f16_f32 v173, v8, v9
	v_mul_f32_e32 v150, v11, v11
	v_mul_f32_e32 v151, v13, v13
	v_fmac_f32_e32 v150, v10, v10
	v_fmac_f32_e32 v151, v12, v12
	v_add_f32_e32 v152, v150, v151
	v_add_f32_e32 v160, v160, v152
	v_cvt_pk_f16_f32 v174, v10, v11
	v_cvt_pk_f16_f32 v175, v12, v13
	v_mul_f32_e32 v150, v15, v15
	v_mul_f32_e32 v151, v17, v17
	v_fmac_f32_e32 v150, v14, v14
	v_fmac_f32_e32 v151, v16, v16
	v_add_f32_e32 v152, v150, v151
	v_add_f32_e32 v160, v160, v152
	v_cvt_pk_f16_f32 v176, v14, v15
	v_cvt_pk_f16_f32 v177, v16, v17
	global_store_dwordx2 v144, v[170:171], s[10:11]
	global_store_dwordx2 v144, v[172:173], s[10:11] offset:512
	global_store_dwordx2 v144, v[174:175], s[10:11] offset:1024
	global_store_dwordx2 v144, v[176:177], s[10:11] offset:1536
	v_mul_f32_e32 v150, v19, v19
	v_mul_f32_e32 v151, v21, v21
	v_fmac_f32_e32 v150, v18, v18
	v_fmac_f32_e32 v151, v20, v20
	v_add_f32_e32 v161, v150, v151
	v_cvt_pk_f16_f32 v178, v18, v19
	v_cvt_pk_f16_f32 v179, v20, v21
	v_mul_f32_e32 v150, v23, v23
	v_mul_f32_e32 v151, v25, v25
	v_fmac_f32_e32 v150, v22, v22
	v_fmac_f32_e32 v151, v24, v24
	v_add_f32_e32 v152, v150, v151
	v_add_f32_e32 v161, v161, v152
	v_cvt_pk_f16_f32 v180, v22, v23
	v_cvt_pk_f16_f32 v181, v24, v25
	v_mul_f32_e32 v150, v27, v27
	v_mul_f32_e32 v151, v29, v29
	v_fmac_f32_e32 v150, v26, v26
	v_fmac_f32_e32 v151, v28, v28
	v_add_f32_e32 v152, v150, v151
	v_add_f32_e32 v161, v161, v152
	v_cvt_pk_f16_f32 v182, v26, v27
	v_cvt_pk_f16_f32 v183, v28, v29
	v_mul_f32_e32 v150, v31, v31
	v_mul_f32_e32 v151, v33, v33
	v_fmac_f32_e32 v150, v30, v30
	v_fmac_f32_e32 v151, v32, v32
	v_add_f32_e32 v152, v150, v151
	v_add_f32_e32 v161, v161, v152
	v_cvt_pk_f16_f32 v184, v30, v31
	v_cvt_pk_f16_f32 v185, v32, v33
	global_store_dwordx2 v145, v[178:179], s[10:11]
	global_store_dwordx2 v145, v[180:181], s[10:11] offset:512
	global_store_dwordx2 v145, v[182:183], s[10:11] offset:1024
	global_store_dwordx2 v145, v[184:185], s[10:11] offset:1536
	v_mul_f32_e32 v150, v35, v35
	v_mul_f32_e32 v151, v37, v37
	v_fmac_f32_e32 v150, v34, v34
	v_fmac_f32_e32 v151, v36, v36
	v_add_f32_e32 v162, v150, v151
	v_cvt_pk_f16_f32 v170, v34, v35
	v_cvt_pk_f16_f32 v171, v36, v37
	v_mul_f32_e32 v150, v39, v39
	v_mul_f32_e32 v151, v41, v41
	v_fmac_f32_e32 v150, v38, v38
	v_fmac_f32_e32 v151, v40, v40
	v_add_f32_e32 v152, v150, v151
; __device__ void p0_xconv(const Args& a) {
;     ...
;         for (int r = 0; r < 4; ++r) {
;             const int row = row0 + r * nwv;
;             if (row < MROWS) {
;                 float ss = 0.f;
; #pragma unroll
;                 for (int i = 0; i < 4; ++i) {
;                     const f32x4 x = v[r][i];
;                     ss += (x[0] * x[0] + x[1] * x[1]) + (x[2] * x[2] + x[3] * x[3]);
;                     f16x4 h; h[0] = (f16)x[0]; h[1] = (f16)x[1]; h[2] = (f16)x[2]; h[3] = (f16)x[3];
;                     *(f16x4*)(XH + (size_t)row * DM + i * 256 + lane * 4) = h;
;                 }
; #pragma unroll
;                 for (int o = 1; o < 64; o <<= 1) ss += __shfl_xor(ss, o);
;                 if (lane < 16) SS[(size_t)row * 16 + lane] = (lane == 0) ? ss : 0.f;
	v_add_f32_e32 v162, v162, v152
	v_cvt_pk_f16_f32 v172, v38, v39
	v_cvt_pk_f16_f32 v173, v40, v41
	v_mul_f32_e32 v150, v43, v43
	v_mul_f32_e32 v151, v45, v45
	v_fmac_f32_e32 v150, v42, v42
	v_fmac_f32_e32 v151, v44, v44
	v_add_f32_e32 v152, v150, v151
	v_add_f32_e32 v162, v162, v152
	v_cvt_pk_f16_f32 v174, v42, v43
	v_cvt_pk_f16_f32 v175, v44, v45
	v_mul_f32_e32 v150, v47, v47
	v_mul_f32_e32 v151, v49, v49
	v_fmac_f32_e32 v150, v46, v46
	v_fmac_f32_e32 v151, v48, v48
	v_add_f32_e32 v152, v150, v151
	v_add_f32_e32 v162, v162, v152
	v_cvt_pk_f16_f32 v176, v46, v47
	v_cvt_pk_f16_f32 v177, v48, v49
	global_store_dwordx2 v146, v[170:171], s[10:11]
	global_store_dwordx2 v146, v[172:173], s[10:11] offset:512
	global_store_dwordx2 v146, v[174:175], s[10:11] offset:1024
	global_store_dwordx2 v146, v[176:177], s[10:11] offset:1536
	v_mul_f32_e32 v150, v51, v51
	v_mul_f32_e32 v151, v53, v53
	v_fmac_f32_e32 v150, v50, v50
	v_fmac_f32_e32 v151, v52, v52
	v_add_f32_e32 v163, v150, v151
	v_cvt_pk_f16_f32 v178, v50, v51
	v_cvt_pk_f16_f32 v179, v52, v53
	v_mul_f32_e32 v150, v55, v55
	v_mul_f32_e32 v151, v57, v57
	v_fmac_f32_e32 v150, v54, v54
	v_fmac_f32_e32 v151, v56, v56
	v_add_f32_e32 v152, v150, v151
	v_add_f32_e32 v163, v163, v152
	v_cvt_pk_f16_f32 v180, v54, v55
	v_cvt_pk_f16_f32 v181, v56, v57
	v_mul_f32_e32 v150, v59, v59
	v_mul_f32_e32 v151, v61, v61
	v_fmac_f32_e32 v150, v58, v58
	v_fmac_f32_e32 v151, v60, v60
	v_add_f32_e32 v152, v150, v151
	v_add_f32_e32 v163, v163, v152
	v_cvt_pk_f16_f32 v182, v58, v59
	v_cvt_pk_f16_f32 v183, v60, v61
	v_mul_f32_e32 v150, v63, v63
	v_mul_f32_e32 v151, v65, v65
	v_fmac_f32_e32 v150, v62, v62
	v_fmac_f32_e32 v151, v64, v64
	v_add_f32_e32 v152, v150, v151
	v_add_f32_e32 v163, v163, v152
	v_cvt_pk_f16_f32 v184, v62, v63
	v_cvt_pk_f16_f32 v185, v64, v65
	global_store_dwordx2 v147, v[178:179], s[10:11]
	global_store_dwordx2 v147, v[180:181], s[10:11] offset:512
	global_store_dwordx2 v147, v[182:183], s[10:11] offset:1024
	global_store_dwordx2 v147, v[184:185], s[10:11] offset:1536
	ds_bpermute_b32 v164, v130, v160
	ds_bpermute_b32 v165, v130, v161
	ds_bpermute_b32 v166, v130, v162
	ds_bpermute_b32 v167, v130, v163
	s_waitcnt lgkmcnt(0)
	v_add_f32_e32 v160, v160, v164
	v_add_f32_e32 v161, v161, v165
	v_add_f32_e32 v162, v162, v166
	v_add_f32_e32 v163, v163, v167
	ds_bpermute_b32 v164, v131, v160
	ds_bpermute_b32 v165, v131, v161
	ds_bpermute_b32 v166, v131, v162
	ds_bpermute_b32 v167, v131, v163
	s_waitcnt lgkmcnt(0)
	v_add_f32_e32 v160, v160, v164
	v_add_f32_e32 v161, v161, v165
	v_add_f32_e32 v162, v162, v166
	v_add_f32_e32 v163, v163, v167
	ds_bpermute_b32 v164, v132, v160
	ds_bpermute_b32 v165, v132, v161
	ds_bpermute_b32 v166, v132, v162
	ds_bpermute_b32 v167, v132, v163
	s_waitcnt lgkmcnt(0)
	v_add_f32_e32 v160, v160, v164
	v_add_f32_e32 v161, v161, v165
	v_add_f32_e32 v162, v162, v166
	v_add_f32_e32 v163, v163, v167
	ds_bpermute_b32 v164, v133, v160
	ds_bpermute_b32 v165, v133, v161
	ds_bpermute_b32 v166, v133, v162
	ds_bpermute_b32 v167, v133, v163
	s_waitcnt lgkmcnt(0)
	v_add_f32_e32 v160, v160, v164
	v_add_f32_e32 v161, v161, v165
	v_add_f32_e32 v162, v162, v166
	v_add_f32_e32 v163, v163, v167
	ds_bpermute_b32 v164, v134, v160
	ds_bpermute_b32 v165, v134, v161
	ds_bpermute_b32 v166, v134, v162
	ds_bpermute_b32 v167, v134, v163
	s_waitcnt lgkmcnt(0)
	v_add_f32_e32 v160, v160, v164
	v_add_f32_e32 v161, v161, v165
	v_add_f32_e32 v162, v162, v166
	v_add_f32_e32 v163, v163, v167
	ds_bpermute_b32 v164, v135, v160
	ds_bpermute_b32 v165, v135, v161
	ds_bpermute_b32 v166, v135, v162
	ds_bpermute_b32 v167, v135, v163
	s_waitcnt lgkmcnt(0)
	v_add_f32_e32 v160, v160, v164
	v_add_f32_e32 v161, v161, v165
	v_add_f32_e32 v162, v162, v166
	v_add_f32_e32 v163, v163, v167
	v_cndmask_b32_e64 v164, 0, v160, s[12:13]
	v_cndmask_b32_e64 v165, 0, v161, s[12:13]
	v_cndmask_b32_e64 v166, 0, v162, s[12:13]
	v_cndmask_b32_e64 v167, 0, v163, s[12:13]
	s_mov_b64 exec, 0xffff
	global_store_dword v186, v164, s[6:7]
	global_store_dword v187, v165, s[6:7]
	global_store_dword v188, v166, s[6:7]
	global_store_dword v189, v167, s[6:7]
	s_mov_b64 exec, -1
	s_waitcnt vmcnt(20)
	s_add_i32 s6, s3, 0x7000
	s_lshl_b32 s7, s6, 11
	s_add_u32 s10, s40, s7
	s_addc_u32 s11, s41, 0
	s_lshl_b32 s7, s6, 6
	s_add_u32 s6, s40, s7
	s_addc_u32 s7, s41, 0
	s_add_u32 s6, s6, 0x1f800000
	s_addc_u32 s7, s7, 0
	v_mul_f32_e32 v150, v67, v67
	v_mul_f32_e32 v151, v69, v69
	v_fmac_f32_e32 v150, v66, v66
	v_fmac_f32_e32 v151, v68, v68
	v_add_f32_e32 v160, v150, v151
	v_cvt_pk_f16_f32 v170, v66, v67
	v_cvt_pk_f16_f32 v171, v68, v69
	v_mul_f32_e32 v150, v71, v71
	v_mul_f32_e32 v151, v73, v73
	v_fmac_f32_e32 v150, v70, v70
	v_fmac_f32_e32 v151, v72, v72
	v_add_f32_e32 v152, v150, v151
	v_add_f32_e32 v160, v160, v152
	v_cvt_pk_f16_f32 v172, v70, v71
	v_cvt_pk_f16_f32 v173, v72, v73
	v_mul_f32_e32 v150, v75, v75
	v_mul_f32_e32 v151, v77, v77
	v_fmac_f32_e32 v150, v74, v74
	v_fmac_f32_e32 v151, v76, v76
	v_add_f32_e32 v152, v150, v151
	v_add_f32_e32 v160, v160, v152
	v_cvt_pk_f16_f32 v174, v74, v75
	v_cvt_pk_f16_f32 v175, v76, v77
	v_mul_f32_e32 v150, v79, v79
	v_mul_f32_e32 v151, v81, v81
	v_fmac_f32_e32 v150, v78, v78
	v_fmac_f32_e32 v151, v80, v80
	v_add_f32_e32 v152, v150, v151
	v_add_f32_e32 v160, v160, v152
	v_cvt_pk_f16_f32 v176, v78, v79
	v_cvt_pk_f16_f32 v177, v80, v81
	global_store_dwordx2 v144, v[170:171], s[10:11]
	global_store_dwordx2 v144, v[172:173], s[10:11] offset:512
	global_store_dwordx2 v144, v[174:175], s[10:11] offset:1024
	global_store_dwordx2 v144, v[176:177], s[10:11] offset:1536
	v_mul_f32_e32 v150, v83, v83
	v_mul_f32_e32 v151, v85, v85
; __device__ void p0_xconv(const Args& a) {
;     ...
;         for (int r = 0; r < 4; ++r) {
;             const int row = row0 + r * nwv;
;             if (row < MROWS) {
;                 float ss = 0.f;
; #pragma unroll
;                 for (int i = 0; i < 4; ++i) {
;                     const f32x4 x = v[r][i];
;                     ss += (x[0] * x[0] + x[1] * x[1]) + (x[2] * x[2] + x[3] * x[3]);
;                     f16x4 h; h[0] = (f16)x[0]; h[1] = (f16)x[1]; h[2] = (f16)x[2]; h[3] = (f16)x[3];
;                     *(f16x4*)(XH + (size_t)row * DM + i * 256 + lane * 4) = h;
;                 }
; #pragma unroll
;                 for (int o = 1; o < 64; o <<= 1) ss += __shfl_xor(ss, o);
;                 if (lane < 16) SS[(size_t)row * 16 + lane] = (lane == 0) ? ss : 0.f;
	v_fmac_f32_e32 v150, v82, v82
	v_fmac_f32_e32 v151, v84, v84
	v_add_f32_e32 v161, v150, v151
	v_cvt_pk_f16_f32 v178, v82, v83
	v_cvt_pk_f16_f32 v179, v84, v85
	v_mul_f32_e32 v150, v87, v87
	v_mul_f32_e32 v151, v89, v89
	v_fmac_f32_e32 v150, v86, v86
	v_fmac_f32_e32 v151, v88, v88
	v_add_f32_e32 v152, v150, v151
	v_add_f32_e32 v161, v161, v152
	v_cvt_pk_f16_f32 v180, v86, v87
	v_cvt_pk_f16_f32 v181, v88, v89
	v_mul_f32_e32 v150, v91, v91
	v_mul_f32_e32 v151, v93, v93
	v_fmac_f32_e32 v150, v90, v90
	v_fmac_f32_e32 v151, v92, v92
	v_add_f32_e32 v152, v150, v151
	v_add_f32_e32 v161, v161, v152
	v_cvt_pk_f16_f32 v182, v90, v91
	v_cvt_pk_f16_f32 v183, v92, v93
	v_mul_f32_e32 v150, v95, v95
	v_mul_f32_e32 v151, v97, v97
	v_fmac_f32_e32 v150, v94, v94
	v_fmac_f32_e32 v151, v96, v96
	v_add_f32_e32 v152, v150, v151
	v_add_f32_e32 v161, v161, v152
	v_cvt_pk_f16_f32 v184, v94, v95
	v_cvt_pk_f16_f32 v185, v96, v97
	global_store_dwordx2 v145, v[178:179], s[10:11]
	global_store_dwordx2 v145, v[180:181], s[10:11] offset:512
	global_store_dwordx2 v145, v[182:183], s[10:11] offset:1024
	global_store_dwordx2 v145, v[184:185], s[10:11] offset:1536
	v_mul_f32_e32 v150, v99, v99
	v_mul_f32_e32 v151, v101, v101
	v_fmac_f32_e32 v150, v98, v98
	v_fmac_f32_e32 v151, v100, v100
	v_add_f32_e32 v162, v150, v151
	v_cvt_pk_f16_f32 v170, v98, v99
	v_cvt_pk_f16_f32 v171, v100, v101
	v_mul_f32_e32 v150, v103, v103
	v_mul_f32_e32 v151, v105, v105
	v_fmac_f32_e32 v150, v102, v102
	v_fmac_f32_e32 v151, v104, v104
	v_add_f32_e32 v152, v150, v151
	v_add_f32_e32 v162, v162, v152
	v_cvt_pk_f16_f32 v172, v102, v103
	v_cvt_pk_f16_f32 v173, v104, v105
	v_mul_f32_e32 v150, v107, v107
	v_mul_f32_e32 v151, v109, v109
	v_fmac_f32_e32 v150, v106, v106
	v_fmac_f32_e32 v151, v108, v108
	v_add_f32_e32 v152, v150, v151
	v_add_f32_e32 v162, v162, v152
	v_cvt_pk_f16_f32 v174, v106, v107
	v_cvt_pk_f16_f32 v175, v108, v109
	v_mul_f32_e32 v150, v111, v111
	v_mul_f32_e32 v151, v113, v113
	v_fmac_f32_e32 v150, v110, v110
	v_fmac_f32_e32 v151, v112, v112
	v_add_f32_e32 v152, v150, v151
	v_add_f32_e32 v162, v162, v152
	v_cvt_pk_f16_f32 v176, v110, v111
	v_cvt_pk_f16_f32 v177, v112, v113
	global_store_dwordx2 v146, v[170:171], s[10:11]
	global_store_dwordx2 v146, v[172:173], s[10:11] offset:512
	global_store_dwordx2 v146, v[174:175], s[10:11] offset:1024
	global_store_dwordx2 v146, v[176:177], s[10:11] offset:1536
	v_mul_f32_e32 v150, v115, v115
	v_mul_f32_e32 v151, v117, v117
	v_fmac_f32_e32 v150, v114, v114
	v_fmac_f32_e32 v151, v116, v116
	v_add_f32_e32 v163, v150, v151
	v_cvt_pk_f16_f32 v178, v114, v115
	v_cvt_pk_f16_f32 v179, v116, v117
	v_mul_f32_e32 v150, v119, v119
	v_mul_f32_e32 v151, v121, v121
	v_fmac_f32_e32 v150, v118, v118
	v_fmac_f32_e32 v151, v120, v120
	v_add_f32_e32 v152, v150, v151
	v_add_f32_e32 v163, v163, v152
	v_cvt_pk_f16_f32 v180, v118, v119
	v_cvt_pk_f16_f32 v181, v120, v121
	v_mul_f32_e32 v150, v123, v123
	v_mul_f32_e32 v151, v125, v125
	v_fmac_f32_e32 v150, v122, v122
	v_fmac_f32_e32 v151, v124, v124
	v_add_f32_e32 v152, v150, v151
	v_add_f32_e32 v163, v163, v152
	v_cvt_pk_f16_f32 v182, v122, v123
	v_cvt_pk_f16_f32 v183, v124, v125
	v_mul_f32_e32 v150, v127, v127
	v_mul_f32_e32 v151, v129, v129
	v_fmac_f32_e32 v150, v126, v126
	v_fmac_f32_e32 v151, v128, v128
	v_add_f32_e32 v152, v150, v151
	v_add_f32_e32 v163, v163, v152
	v_cvt_pk_f16_f32 v184, v126, v127
	v_cvt_pk_f16_f32 v185, v128, v129
	global_store_dwordx2 v147, v[178:179], s[10:11]
	global_store_dwordx2 v147, v[180:181], s[10:11] offset:512
	global_store_dwordx2 v147, v[182:183], s[10:11] offset:1024
	global_store_dwordx2 v147, v[184:185], s[10:11] offset:1536
	ds_bpermute_b32 v164, v130, v160
	ds_bpermute_b32 v165, v130, v161
	ds_bpermute_b32 v166, v130, v162
	ds_bpermute_b32 v167, v130, v163
	s_waitcnt lgkmcnt(0)
	v_add_f32_e32 v160, v160, v164
	v_add_f32_e32 v161, v161, v165
	v_add_f32_e32 v162, v162, v166
	v_add_f32_e32 v163, v163, v167
	ds_bpermute_b32 v164, v131, v160
	ds_bpermute_b32 v165, v131, v161
	ds_bpermute_b32 v166, v131, v162
	ds_bpermute_b32 v167, v131, v163
	s_waitcnt lgkmcnt(0)
	v_add_f32_e32 v160, v160, v164
	v_add_f32_e32 v161, v161, v165
	v_add_f32_e32 v162, v162, v166
	v_add_f32_e32 v163, v163, v167
	ds_bpermute_b32 v164, v132, v160
	ds_bpermute_b32 v165, v132, v161
	ds_bpermute_b32 v166, v132, v162
	ds_bpermute_b32 v167, v132, v163
	s_waitcnt lgkmcnt(0)
	v_add_f32_e32 v160, v160, v164
	v_add_f32_e32 v161, v161, v165
	v_add_f32_e32 v162, v162, v166
	v_add_f32_e32 v163, v163, v167
	ds_bpermute_b32 v164, v133, v160
	ds_bpermute_b32 v165, v133, v161
	ds_bpermute_b32 v166, v133, v162
	ds_bpermute_b32 v167, v133, v163
	s_waitcnt lgkmcnt(0)
	v_add_f32_e32 v160, v160, v164
	v_add_f32_e32 v161, v161, v165
	v_add_f32_e32 v162, v162, v166
	v_add_f32_e32 v163, v163, v167
	ds_bpermute_b32 v164, v134, v160
	ds_bpermute_b32 v165, v134, v161
	ds_bpermute_b32 v166, v134, v162
	ds_bpermute_b32 v167, v134, v163
	s_waitcnt lgkmcnt(0)
	v_add_f32_e32 v160, v160, v164
	v_add_f32_e32 v161, v161, v165
	v_add_f32_e32 v162, v162, v166
	v_add_f32_e32 v163, v163, v167
	ds_bpermute_b32 v164, v135, v160
	ds_bpermute_b32 v165, v135, v161
	ds_bpermute_b32 v166, v135, v162
	ds_bpermute_b32 v167, v135, v163
	s_waitcnt lgkmcnt(0)
	v_add_f32_e32 v160, v160, v164
	v_add_f32_e32 v161, v161, v165
	v_add_f32_e32 v162, v162, v166
	v_add_f32_e32 v163, v163, v167
	v_cndmask_b32_e64 v164, 0, v160, s[12:13]
	v_cndmask_b32_e64 v165, 0, v161, s[12:13]
	v_cndmask_b32_e64 v166, 0, v162, s[12:13]
	v_cndmask_b32_e64 v167, 0, v163, s[12:13]
	s_mov_b64 exec, 0xffff
	global_store_dword v186, v164, s[6:7]
	global_store_dword v187, v165, s[6:7]
	global_store_dword v188, v166, s[6:7]
	global_store_dword v189, v167, s[6:7]
	s_mov_b64 exec, -1
	s_branch .LBB0_37
